# layer-0 norm and final norm: wave all-reduce via DPP adds + permlane swaps as in the other norm loops (strategy 7 extended)
# baseline (speedup 1.0000x reference)
.LBB0_267:
	global_load_dwordx4 v[88:91], v[158:159], off offset:-4096
	v_lshl_add_u64 v[0:1], s[12:13], 0, v[148:149]
	v_add_co_u32_e32 v4, vcc, 0x3000000, v0
	s_add_i32 s16, s6, 1
	s_nop 0
	v_addc_co_u32_e32 v5, vcc, 0, v1, vcc
	s_ashr_i32 s17, s16, 31
	s_lshl_b64 s[18:19], s[16:17], 13
	s_lshl_b64 s[16:17], s[16:17], 12
	s_waitcnt vmcnt(0)
	v_lshl_add_u64 v[16:17], v[150:151], 0, s[16:17]
	s_ashr_i32 s5, s6, 31
	s_lshr_b32 s5, s5, 20
	s_add_i32 s5, s6, s5
	s_ashr_i32 s5, s5, 12
	s_waitcnt vmcnt(0)
	v_cvt_pk_f16_f32 v3, v90, v91
	v_cvt_pk_f16_f32 v2, v88, v89
	global_store_dwordx2 v[4:5], v[2:3], off
	global_load_dwordx4 v[72:75], v[158:159], off offset:-3072
	v_mov_b32_e32 v132, v91
	s_waitcnt vmcnt(0)
	v_cvt_pk_f16_f32 v1, v74, v75
	v_cvt_pk_f16_f32 v0, v72, v73
	global_store_dwordx2 v[4:5], v[0:1], off offset:512
	global_load_dwordx4 v[68:71], v[158:159], off offset:-2048
	v_mov_b32_e32 v133, v75
	v_pk_mul_f32 v[132:133], v[132:133], v[132:133]
	s_waitcnt vmcnt(0)
	v_cvt_pk_f16_f32 v1, v70, v71
	v_cvt_pk_f16_f32 v0, v68, v69
	global_store_dwordx2 v[4:5], v[0:1], off offset:1024
	global_load_dwordx4 v[64:67], v[158:159], off offset:-1024
	s_waitcnt vmcnt(0)
	v_cvt_pk_f16_f32 v1, v66, v67
	v_cvt_pk_f16_f32 v0, v64, v65
	global_store_dwordx2 v[4:5], v[0:1], off offset:1536
	global_load_dwordx4 v[48:51], v[158:159], off
	s_waitcnt vmcnt(0)
	v_cvt_pk_f16_f32 v1, v50, v51
	v_cvt_pk_f16_f32 v0, v48, v49
	global_store_dwordx2 v[4:5], v[0:1], off offset:2048
	global_load_dwordx4 v[44:47], v[158:159], off offset:1024
	s_waitcnt vmcnt(0)
	v_cvt_pk_f16_f32 v1, v46, v47
	v_cvt_pk_f16_f32 v0, v44, v45
	global_store_dwordx2 v[4:5], v[0:1], off offset:2560
	global_load_dwordx4 v[8:11], v[158:159], off offset:2048
	s_waitcnt vmcnt(0)
	v_cvt_pk_f16_f32 v1, v10, v11
	v_cvt_pk_f16_f32 v0, v8, v9
	global_store_dwordx2 v[4:5], v[0:1], off offset:3072
	global_load_dwordx4 v[0:3], v[158:159], off offset:3072
	v_lshl_add_u64 v[158:159], v[158:159], 0, s[14:15]
	s_waitcnt vmcnt(0)
	v_cvt_pk_f16_f32 v7, v2, v3
	v_cvt_pk_f16_f32 v6, v0, v1
	global_store_dwordx2 v[4:5], v[6:7], off offset:3584
	v_lshl_add_u64 v[4:5], v[146:147], 0, s[18:19]
	global_load_dwordx4 v[100:103], v[4:5], off
	s_add_i32 s18, s6, 2
	s_ashr_i32 s19, s18, 31
	s_lshl_b64 s[22:23], s[18:19], 13
	s_lshl_b64 s[18:19], s[18:19], 12
	v_lshl_add_u64 v[24:25], v[150:151], 0, s[18:19]
	s_waitcnt vmcnt(0)
	v_cvt_pk_f16_f32 v7, v102, v103
	v_cvt_pk_f16_f32 v6, v100, v101
	global_store_dwordx2 v[16:17], v[6:7], off
	global_load_dwordx4 v[84:87], v[4:5], off offset:1024
	s_waitcnt vmcnt(0)
	v_cvt_pk_f16_f32 v7, v86, v87
	v_cvt_pk_f16_f32 v6, v84, v85
	global_store_dwordx2 v[16:17], v[6:7], off offset:512
	global_load_dwordx4 v[80:83], v[4:5], off offset:2048
	s_waitcnt vmcnt(0)
	v_cvt_pk_f16_f32 v7, v82, v83
	v_cvt_pk_f16_f32 v6, v80, v81
	global_store_dwordx2 v[16:17], v[6:7], off offset:1024
	global_load_dwordx4 v[76:79], v[4:5], off offset:3072
	v_add_co_u32_e32 v4, vcc, s77, v4
	s_waitcnt vmcnt(0)
	v_cvt_pk_f16_f32 v7, v78, v79
	v_cvt_pk_f16_f32 v6, v76, v77
	global_store_dwordx2 v[16:17], v[6:7], off offset:1536
	v_addc_co_u32_e32 v5, vcc, 0, v5, vcc
	global_load_dwordx4 v[52:55], v[4:5], off
	s_waitcnt vmcnt(0)
	v_cvt_pk_f16_f32 v7, v54, v55
	v_cvt_pk_f16_f32 v6, v52, v53
	global_store_dwordx2 v[16:17], v[6:7], off offset:2048
	global_load_dwordx4 v[40:43], v[4:5], off offset:1024
	s_waitcnt vmcnt(0)
	v_cvt_pk_f16_f32 v7, v42, v43
	v_cvt_pk_f16_f32 v6, v40, v41
	global_store_dwordx2 v[16:17], v[6:7], off offset:2560
	global_load_dwordx4 v[12:15], v[4:5], off offset:2048
	s_waitcnt vmcnt(0)
	v_cvt_pk_f16_f32 v7, v14, v15
	v_cvt_pk_f16_f32 v6, v12, v13
	global_store_dwordx2 v[16:17], v[6:7], off offset:3072
	global_load_dwordx4 v[4:7], v[4:5], off offset:3072
	s_waitcnt vmcnt(0)
	v_cvt_pk_f16_f32 v19, v6, v7
	v_cvt_pk_f16_f32 v18, v4, v5
	global_store_dwordx2 v[16:17], v[18:19], off offset:3584
	v_lshl_add_u64 v[16:17], v[146:147], 0, s[22:23]
	global_load_dwordx4 v[108:111], v[16:17], off
	s_add_i32 s22, s6, 3
	s_ashr_i32 s23, s22, 31
	s_lshl_b64 s[52:53], s[22:23], 13
	s_lshl_b64 s[22:23], s[22:23], 12
	v_lshl_add_u64 v[128:129], v[150:151], 0, s[22:23]
	s_add_i32 s6, s6, s4
	s_cmp_lt_i32 s6, s20
	s_waitcnt vmcnt(0)
	v_cvt_pk_f16_f32 v19, v110, v111
	v_cvt_pk_f16_f32 v18, v108, v109
	global_store_dwordx2 v[24:25], v[18:19], off
	global_load_dwordx4 v[104:107], v[16:17], off offset:1024
	s_waitcnt vmcnt(0)
	v_cvt_pk_f16_f32 v19, v106, v107
	v_cvt_pk_f16_f32 v18, v104, v105
	global_store_dwordx2 v[24:25], v[18:19], off offset:512
	global_load_dwordx4 v[96:99], v[16:17], off offset:2048
	s_waitcnt vmcnt(0)
	v_cvt_pk_f16_f32 v19, v98, v99
	v_cvt_pk_f16_f32 v18, v96, v97
	global_store_dwordx2 v[24:25], v[18:19], off offset:1024
	global_load_dwordx4 v[92:95], v[16:17], off offset:3072
	v_add_co_u32_e32 v16, vcc, s77, v16
	s_waitcnt vmcnt(0)
	v_cvt_pk_f16_f32 v19, v94, v95
	v_cvt_pk_f16_f32 v18, v92, v93
	global_store_dwordx2 v[24:25], v[18:19], off offset:1536
	v_addc_co_u32_e32 v17, vcc, 0, v17, vcc
	global_load_dwordx4 v[56:59], v[16:17], off
	s_waitcnt vmcnt(0)
	v_cvt_pk_f16_f32 v19, v58, v59
	v_cvt_pk_f16_f32 v18, v56, v57
	global_store_dwordx2 v[24:25], v[18:19], off offset:2048
	global_load_dwordx4 v[36:39], v[16:17], off offset:1024
	s_waitcnt vmcnt(0)
	v_cvt_pk_f16_f32 v19, v38, v39
	v_cvt_pk_f16_f32 v18, v36, v37
	global_store_dwordx2 v[24:25], v[18:19], off offset:2560
	global_load_dwordx4 v[20:23], v[16:17], off offset:2048
	s_waitcnt vmcnt(0)
	v_cvt_pk_f16_f32 v19, v22, v23
	v_cvt_pk_f16_f32 v18, v20, v21
	global_store_dwordx2 v[24:25], v[18:19], off offset:3072
	global_load_dwordx4 v[16:19], v[16:17], off offset:3072
	s_waitcnt vmcnt(0)
	v_cvt_pk_f16_f32 v27, v18, v19
	v_cvt_pk_f16_f32 v26, v16, v17
	global_store_dwordx2 v[24:25], v[26:27], off offset:3584
	v_lshl_add_u64 v[24:25], v[146:147], 0, s[52:53]
	global_load_dwordx4 v[124:127], v[24:25], off
	v_mad_i64_i32 v[170:171], s[52:53], s5, v237, v[152:153]
	v_mad_i64_i32 v[168:169], s[52:53], s5, v237, v[154:155]
	s_waitcnt vmcnt(0)
	v_cvt_pk_f16_f32 v27, v126, v127
	v_cvt_pk_f16_f32 v26, v124, v125
	global_store_dwordx2 v[128:129], v[26:27], off
	global_load_dwordx4 v[120:123], v[24:25], off offset:1024
	s_waitcnt vmcnt(0)
	v_cvt_pk_f16_f32 v27, v122, v123
	v_cvt_pk_f16_f32 v26, v120, v121
	global_store_dwordx2 v[128:129], v[26:27], off offset:512
	global_load_dwordx4 v[116:119], v[24:25], off offset:2048
	s_waitcnt vmcnt(0)
	v_cvt_pk_f16_f32 v27, v118, v119
	v_cvt_pk_f16_f32 v26, v116, v117
	global_store_dwordx2 v[128:129], v[26:27], off offset:1024
	global_load_dwordx4 v[112:115], v[24:25], off offset:3072
	v_add_co_u32_e32 v24, vcc, s77, v24
	s_waitcnt vmcnt(0)
	v_cvt_pk_f16_f32 v27, v114, v115
	v_cvt_pk_f16_f32 v26, v112, v113
	global_store_dwordx2 v[128:129], v[26:27], off offset:1536
	v_addc_co_u32_e32 v25, vcc, 0, v25, vcc
	global_load_dwordx4 v[60:63], v[24:25], off
	s_waitcnt vmcnt(0)
	v_cvt_pk_f16_f32 v27, v62, v63
	v_cvt_pk_f16_f32 v26, v60, v61
	global_store_dwordx2 v[128:129], v[26:27], off offset:2048
	global_load_dwordx4 v[32:35], v[24:25], off offset:1024
	s_waitcnt vmcnt(0)
	v_cvt_pk_f16_f32 v27, v34, v35
	v_cvt_pk_f16_f32 v26, v32, v33
	global_store_dwordx2 v[128:129], v[26:27], off offset:2560
	global_load_dwordx4 v[28:31], v[24:25], off offset:2048
	s_waitcnt vmcnt(0)
	v_cvt_pk_f16_f32 v27, v30, v31
	v_cvt_pk_f16_f32 v26, v28, v29
	global_store_dwordx2 v[128:129], v[26:27], off offset:3072
	global_load_dwordx4 v[24:27], v[24:25], off offset:3072
	s_waitcnt vmcnt(0)
	v_cvt_pk_f16_f32 v131, v26, v27
	v_cvt_pk_f16_f32 v130, v24, v25
	global_store_dwordx2 v[128:129], v[130:131], off offset:3584
	v_mov_b32_e32 v130, v89
	v_mov_b32_e32 v131, v73
	v_mov_b32_e32 v128, v88
	v_mov_b32_e32 v129, v72
	v_pk_mul_f32 v[130:131], v[130:131], v[130:131]
	s_nop 0
	v_pk_fma_f32 v[128:129], v[128:129], v[128:129], v[130:131]
	v_mov_b32_e32 v130, v90
	v_mov_b32_e32 v131, v74
	v_pk_fma_f32 v[130:131], v[130:131], v[130:131], v[132:133]
	v_pk_mul_f32 v[132:133], v[68:69], v[68:69]
	v_pk_add_f32 v[128:129], v[128:129], v[130:131]
	v_pk_mul_f32 v[130:131], v[70:71], v[70:71]
	v_pk_add_f32 v[128:129], v[128:129], v[128:129] op_sel:[0,1] op_sel_hi:[1,0]
	v_pk_mov_b32 v[134:135], v[132:133], v[130:131] op_sel:[1,0]
	v_mov_b32_e32 v133, v131
	v_pk_add_f32 v[130:131], v[134:135], v[132:133]
	v_mul_f32_e32 v132, v48, v48
	v_mul_f32_e32 v133, v49, v49
	v_pk_add_f32 v[130:131], v[130:131], v[130:131] op_sel:[0,1] op_sel_hi:[1,0]
	v_mov_b32_e32 v129, v132
	v_mov_b32_e32 v131, v133
	v_pk_add_f32 v[128:129], v[128:129], v[130:131]
	v_mul_f32_e32 v130, v65, v65
	v_mul_f32_e32 v132, v67, v67
	v_mul_f32_e32 v134, v50, v50
	v_mul_f32_e32 v135, v51, v51
	v_pk_fma_f32 v[130:131], v[64:65], v[64:65], v[130:131] op_sel_hi:[1,1,0]
	v_pk_fma_f32 v[132:133], v[66:67], v[66:67], v[132:133] op_sel_hi:[1,1,0]
	v_mov_b32_e32 v131, v134
	v_mov_b32_e32 v133, v135
	v_pk_add_f32 v[130:131], v[130:131], v[132:133]
	v_pk_mul_f32 v[132:133], v[44:45], v[44:45]
	v_pk_add_f32 v[128:129], v[128:129], v[130:131]
	v_pk_mul_f32 v[130:131], v[46:47], v[46:47]
	v_pk_add_f32 v[128:129], v[128:129], v[128:129] op_sel:[0,1] op_sel_hi:[1,0]
	v_pk_mov_b32 v[134:135], v[132:133], v[130:131] op_sel:[1,0]
	v_mov_b32_e32 v133, v131
	v_pk_add_f32 v[130:131], v[134:135], v[132:133]
	v_mul_f32_e32 v132, v0, v0
	v_mul_f32_e32 v133, v1, v1
	v_pk_add_f32 v[130:131], v[130:131], v[130:131] op_sel:[0,1] op_sel_hi:[1,0]
	v_mov_b32_e32 v129, v132
	v_mov_b32_e32 v131, v133
	v_pk_add_f32 v[128:129], v[128:129], v[130:131]
	v_mul_f32_e32 v130, v9, v9
	v_mul_f32_e32 v132, v11, v11
	v_mul_f32_e32 v134, v2, v2
	v_mul_f32_e32 v135, v3, v3
	v_pk_fma_f32 v[130:131], v[8:9], v[8:9], v[130:131] op_sel_hi:[1,1,0]
	v_pk_fma_f32 v[132:133], v[10:11], v[10:11], v[132:133] op_sel_hi:[1,1,0]
	v_mov_b32_e32 v131, v134
	v_mov_b32_e32 v133, v135
	v_pk_add_f32 v[130:131], v[130:131], v[132:133]
	v_mov_b32_e32 v132, v103
	v_pk_add_f32 v[128:129], v[128:129], v[130:131]
	v_mov_b32_e32 v130, v101
	v_add_f32_e32 v128, v128, v129
	v_mov_b32_e32 v131, v85
	v_pk_mul_f32 v[130:131], v[130:131], v[130:131]
	v_mov_b32_e32 v133, v87
	v_pk_mul_f32 v[132:133], v[132:133], v[132:133]
	s_waitcnt lgkmcnt(0)
	s_nop 1
	v_add_f32_dpp v128, v128, v128 quad_perm:[1,0,3,2] row_mask:0xf bank_mask:0xf
	s_waitcnt lgkmcnt(0)
	s_nop 1
	v_add_f32_dpp v128, v128, v128 quad_perm:[2,3,0,1] row_mask:0xf bank_mask:0xf
	s_waitcnt lgkmcnt(0)
	s_nop 1
	v_add_f32_dpp v128, v128, v128 row_half_mirror row_mask:0xf bank_mask:0xf
	s_waitcnt lgkmcnt(0)
	s_nop 1
	v_add_f32_dpp v128, v128, v128 row_mirror row_mask:0xf bank_mask:0xf
	s_waitcnt lgkmcnt(0)
	v_mov_b32_e32 v129, v128
	s_nop 1
	v_permlane16_swap_b32_e32 v128, v129
	s_nop 0
	v_add_f32_e32 v128, v128, v129
	s_waitcnt lgkmcnt(0)
	v_mov_b32_e32 v129, v128
	s_nop 1
	v_permlane32_swap_b32_e32 v128, v129
	s_nop 0
	v_add_f32_e32 v128, v128, v129
	v_fmamk_f32 v128, v128, 0x3a000000, v232
	v_rsq_f32_e32 v160, v128
	v_mov_b32_e32 v128, v100
	v_mov_b32_e32 v129, v84
	v_pk_fma_f32 v[128:129], v[128:129], v[128:129], v[130:131]
	v_mov_b32_e32 v130, v102
	v_mov_b32_e32 v131, v86
	v_pk_fma_f32 v[130:131], v[130:131], v[130:131], v[132:133]
	v_pk_mul_f32 v[132:133], v[80:81], v[80:81]
	v_pk_add_f32 v[128:129], v[128:129], v[130:131]
	v_pk_mul_f32 v[130:131], v[82:83], v[82:83]
	v_pk_add_f32 v[128:129], v[128:129], v[128:129] op_sel:[0,1] op_sel_hi:[1,0]
	v_pk_mov_b32 v[134:135], v[132:133], v[130:131] op_sel:[1,0]
	v_mov_b32_e32 v133, v131
	v_pk_add_f32 v[130:131], v[134:135], v[132:133]
	v_mul_f32_e32 v132, v52, v52
	v_mul_f32_e32 v133, v53, v53
	v_pk_add_f32 v[130:131], v[130:131], v[130:131] op_sel:[0,1] op_sel_hi:[1,0]
	v_mov_b32_e32 v129, v132
	v_mov_b32_e32 v131, v133
	v_pk_add_f32 v[128:129], v[128:129], v[130:131]
	v_mul_f32_e32 v130, v77, v77
	v_mul_f32_e32 v132, v79, v79
	v_mul_f32_e32 v134, v54, v54
	v_mul_f32_e32 v135, v55, v55
	v_pk_fma_f32 v[130:131], v[76:77], v[76:77], v[130:131] op_sel_hi:[1,1,0]
	v_pk_fma_f32 v[132:133], v[78:79], v[78:79], v[132:133] op_sel_hi:[1,1,0]
	v_mov_b32_e32 v131, v134
	v_mov_b32_e32 v133, v135
	v_pk_add_f32 v[130:131], v[130:131], v[132:133]
	v_pk_mul_f32 v[132:133], v[40:41], v[40:41]
	v_pk_add_f32 v[128:129], v[128:129], v[130:131]
	v_pk_mul_f32 v[130:131], v[42:43], v[42:43]
	v_pk_add_f32 v[128:129], v[128:129], v[128:129] op_sel:[0,1] op_sel_hi:[1,0]
	v_pk_mov_b32 v[134:135], v[132:133], v[130:131] op_sel:[1,0]
	v_mov_b32_e32 v133, v131
	v_pk_add_f32 v[130:131], v[134:135], v[132:133]
	v_mul_f32_e32 v132, v4, v4
	v_mul_f32_e32 v133, v5, v5
	v_pk_add_f32 v[130:131], v[130:131], v[130:131] op_sel:[0,1] op_sel_hi:[1,0]
	v_mov_b32_e32 v129, v132
	v_mov_b32_e32 v131, v133
	v_pk_add_f32 v[128:129], v[128:129], v[130:131]
	v_mul_f32_e32 v130, v13, v13
	v_mul_f32_e32 v132, v15, v15
	v_mul_f32_e32 v134, v6, v6
	v_mul_f32_e32 v135, v7, v7
	v_pk_fma_f32 v[130:131], v[12:13], v[12:13], v[130:131] op_sel_hi:[1,1,0]
	v_pk_fma_f32 v[132:133], v[14:15], v[14:15], v[132:133] op_sel_hi:[1,1,0]
	v_mov_b32_e32 v131, v134
	v_mov_b32_e32 v133, v135
	v_pk_add_f32 v[130:131], v[130:131], v[132:133]
	v_mov_b32_e32 v132, v111
	v_pk_add_f32 v[128:129], v[128:129], v[130:131]
	v_mov_b32_e32 v130, v109
	v_add_f32_e32 v128, v128, v129
	v_mov_b32_e32 v131, v105
	v_pk_mul_f32 v[130:131], v[130:131], v[130:131]
	v_mov_b32_e32 v133, v107
	v_pk_mul_f32 v[132:133], v[132:133], v[132:133]
	s_waitcnt lgkmcnt(0)
	s_nop 1
	v_add_f32_dpp v128, v128, v128 quad_perm:[1,0,3,2] row_mask:0xf bank_mask:0xf
	v_pk_mul_f32 v[90:91], v[90:91], v[160:161] op_sel_hi:[1,0]
	v_pk_mul_f32 v[88:89], v[88:89], v[160:161] op_sel_hi:[1,0]
	v_pk_mul_f32 v[74:75], v[74:75], v[160:161] op_sel_hi:[1,0]
	v_pk_mul_f32 v[72:73], v[72:73], v[160:161] op_sel_hi:[1,0]
	s_waitcnt lgkmcnt(0)
	s_nop 1
	v_add_f32_dpp v128, v128, v128 quad_perm:[2,3,0,1] row_mask:0xf bank_mask:0xf
	v_pk_mul_f32 v[70:71], v[70:71], v[160:161] op_sel_hi:[1,0]
	v_pk_mul_f32 v[68:69], v[68:69], v[160:161] op_sel_hi:[1,0]
	v_pk_mul_f32 v[66:67], v[66:67], v[160:161] op_sel_hi:[1,0]
	v_pk_mul_f32 v[64:65], v[64:65], v[160:161] op_sel_hi:[1,0]
	s_waitcnt lgkmcnt(0)
	s_nop 1
	v_add_f32_dpp v128, v128, v128 row_half_mirror row_mask:0xf bank_mask:0xf
	v_pk_mul_f32 v[50:51], v[50:51], v[160:161] op_sel_hi:[1,0]
	v_pk_mul_f32 v[48:49], v[48:49], v[160:161] op_sel_hi:[1,0]
	v_pk_mul_f32 v[46:47], v[46:47], v[160:161] op_sel_hi:[1,0]
	v_pk_mul_f32 v[44:45], v[44:45], v[160:161] op_sel_hi:[1,0]
	s_waitcnt lgkmcnt(0)
	s_nop 1
	v_add_f32_dpp v128, v128, v128 row_mirror row_mask:0xf bank_mask:0xf
	v_pk_mul_f32 v[10:11], v[10:11], v[160:161] op_sel_hi:[1,0]
	v_pk_mul_f32 v[8:9], v[8:9], v[160:161] op_sel_hi:[1,0]
	v_pk_mul_f32 v[2:3], v[2:3], v[160:161] op_sel_hi:[1,0]
	v_pk_mul_f32 v[0:1], v[0:1], v[160:161] op_sel_hi:[1,0]
	s_waitcnt lgkmcnt(0)
	v_mov_b32_e32 v129, v128
	s_nop 1
	v_permlane16_swap_b32_e32 v128, v129
	s_nop 0
	v_add_f32_e32 v128, v128, v129
	s_waitcnt lgkmcnt(0)
	v_mov_b32_e32 v129, v128
	s_nop 1
	v_permlane32_swap_b32_e32 v128, v129
	s_nop 0
	v_add_f32_e32 v128, v128, v129
	v_fmamk_f32 v128, v128, 0x3a000000, v232
	v_rsq_f32_e32 v162, v128
	v_mov_b32_e32 v128, v108
	v_mov_b32_e32 v129, v104
	v_pk_fma_f32 v[128:129], v[128:129], v[128:129], v[130:131]
	v_mov_b32_e32 v130, v110
	v_mov_b32_e32 v131, v106
	v_pk_fma_f32 v[130:131], v[130:131], v[130:131], v[132:133]
	v_pk_mul_f32 v[132:133], v[96:97], v[96:97]
	v_pk_add_f32 v[128:129], v[128:129], v[130:131]
	v_pk_mul_f32 v[130:131], v[98:99], v[98:99]
	v_pk_add_f32 v[128:129], v[128:129], v[128:129] op_sel:[0,1] op_sel_hi:[1,0]
	v_pk_mov_b32 v[134:135], v[132:133], v[130:131] op_sel:[1,0]
	v_mov_b32_e32 v133, v131
	v_pk_add_f32 v[130:131], v[134:135], v[132:133]
	v_mul_f32_e32 v132, v56, v56
	v_mul_f32_e32 v133, v57, v57
	v_pk_add_f32 v[130:131], v[130:131], v[130:131] op_sel:[0,1] op_sel_hi:[1,0]
	v_mov_b32_e32 v129, v132
	v_mov_b32_e32 v131, v133
	v_pk_add_f32 v[128:129], v[128:129], v[130:131]
	v_mul_f32_e32 v130, v93, v93
	v_mul_f32_e32 v132, v95, v95
	v_mul_f32_e32 v134, v58, v58
	v_mul_f32_e32 v135, v59, v59
	v_pk_fma_f32 v[130:131], v[92:93], v[92:93], v[130:131] op_sel_hi:[1,1,0]
	v_pk_fma_f32 v[132:133], v[94:95], v[94:95], v[132:133] op_sel_hi:[1,1,0]
	v_mov_b32_e32 v131, v134
	v_mov_b32_e32 v133, v135
	v_pk_add_f32 v[130:131], v[130:131], v[132:133]
	v_pk_mul_f32 v[132:133], v[36:37], v[36:37]
	v_pk_add_f32 v[128:129], v[128:129], v[130:131]
	v_pk_mul_f32 v[130:131], v[38:39], v[38:39]
	v_pk_add_f32 v[128:129], v[128:129], v[128:129] op_sel:[0,1] op_sel_hi:[1,0]
	v_pk_mov_b32 v[134:135], v[132:133], v[130:131] op_sel:[1,0]
	v_mov_b32_e32 v133, v131
	v_pk_add_f32 v[130:131], v[134:135], v[132:133]
	v_mul_f32_e32 v132, v16, v16
	v_mul_f32_e32 v133, v17, v17
	v_pk_add_f32 v[130:131], v[130:131], v[130:131] op_sel:[0,1] op_sel_hi:[1,0]
	v_mov_b32_e32 v129, v132
	v_mov_b32_e32 v131, v133
	v_pk_add_f32 v[128:129], v[128:129], v[130:131]
	v_mul_f32_e32 v130, v21, v21
	v_mul_f32_e32 v132, v23, v23
	v_mul_f32_e32 v134, v18, v18
	v_mul_f32_e32 v135, v19, v19
	v_pk_fma_f32 v[130:131], v[20:21], v[20:21], v[130:131] op_sel_hi:[1,1,0]
	v_pk_fma_f32 v[132:133], v[22:23], v[22:23], v[132:133] op_sel_hi:[1,1,0]
	v_mov_b32_e32 v131, v134
	v_mov_b32_e32 v133, v135
	v_pk_add_f32 v[130:131], v[130:131], v[132:133]
	v_mov_b32_e32 v132, v127
	v_pk_add_f32 v[128:129], v[128:129], v[130:131]
	v_mov_b32_e32 v130, v125
	v_add_f32_e32 v128, v128, v129
	v_mov_b32_e32 v131, v121
	v_pk_mul_f32 v[130:131], v[130:131], v[130:131]
	v_mov_b32_e32 v133, v123
	v_pk_mul_f32 v[132:133], v[132:133], v[132:133]
	s_waitcnt lgkmcnt(0)
	s_nop 1
	v_add_f32_dpp v128, v128, v128 quad_perm:[1,0,3,2] row_mask:0xf bank_mask:0xf
	v_pk_mul_f32 v[100:101], v[100:101], v[162:163] op_sel_hi:[1,0]
	v_pk_mul_f32 v[42:43], v[42:43], v[162:163] op_sel_hi:[1,0]
	v_pk_mul_f32 v[40:41], v[40:41], v[162:163] op_sel_hi:[1,0]
	s_waitcnt lgkmcnt(0)
	s_nop 1
	v_add_f32_dpp v128, v128, v128 quad_perm:[2,3,0,1] row_mask:0xf bank_mask:0xf
	s_waitcnt lgkmcnt(0)
	s_nop 1
	v_add_f32_dpp v128, v128, v128 row_half_mirror row_mask:0xf bank_mask:0xf
	s_waitcnt lgkmcnt(0)
	s_nop 1
	v_add_f32_dpp v128, v128, v128 row_mirror row_mask:0xf bank_mask:0xf
	s_waitcnt lgkmcnt(0)
	v_mov_b32_e32 v129, v128
	s_nop 1
	v_permlane16_swap_b32_e32 v128, v129
	s_nop 0
	v_add_f32_e32 v128, v128, v129
	s_waitcnt lgkmcnt(0)
	v_mov_b32_e32 v129, v128
	s_nop 1
	v_permlane32_swap_b32_e32 v128, v129
	s_nop 0
	v_add_f32_e32 v128, v128, v129
	v_fmamk_f32 v128, v128, 0x3a000000, v232
	v_rsq_f32_e32 v164, v128
	v_mov_b32_e32 v128, v124
	v_mov_b32_e32 v129, v120
	v_pk_fma_f32 v[128:129], v[128:129], v[128:129], v[130:131]
	v_mov_b32_e32 v130, v126
	v_mov_b32_e32 v131, v122
	v_pk_fma_f32 v[130:131], v[130:131], v[130:131], v[132:133]
	v_pk_mul_f32 v[132:133], v[116:117], v[116:117]
	v_pk_add_f32 v[128:129], v[128:129], v[130:131]
	v_pk_mul_f32 v[130:131], v[118:119], v[118:119]
	v_pk_add_f32 v[128:129], v[128:129], v[128:129] op_sel:[0,1] op_sel_hi:[1,0]
	v_pk_mov_b32 v[134:135], v[132:133], v[130:131] op_sel:[1,0]
	v_mov_b32_e32 v133, v131
	v_pk_add_f32 v[130:131], v[134:135], v[132:133]
	v_mul_f32_e32 v132, v60, v60
	v_mul_f32_e32 v133, v61, v61
	v_pk_add_f32 v[130:131], v[130:131], v[130:131] op_sel:[0,1] op_sel_hi:[1,0]
	v_mov_b32_e32 v129, v132
	v_mov_b32_e32 v131, v133
	v_pk_add_f32 v[128:129], v[128:129], v[130:131]
	v_mul_f32_e32 v130, v113, v113
	v_mul_f32_e32 v132, v115, v115
	v_mul_f32_e32 v134, v62, v62
	v_mul_f32_e32 v135, v63, v63
	v_pk_fma_f32 v[130:131], v[112:113], v[112:113], v[130:131] op_sel_hi:[1,1,0]
	v_pk_fma_f32 v[132:133], v[114:115], v[114:115], v[132:133] op_sel_hi:[1,1,0]
	v_mov_b32_e32 v131, v134
	v_mov_b32_e32 v133, v135
	v_pk_add_f32 v[130:131], v[130:131], v[132:133]
	v_pk_mul_f32 v[132:133], v[32:33], v[32:33]
	v_pk_add_f32 v[128:129], v[128:129], v[130:131]
	v_pk_mul_f32 v[130:131], v[34:35], v[34:35]
	v_pk_add_f32 v[128:129], v[128:129], v[128:129] op_sel:[0,1] op_sel_hi:[1,0]
	v_pk_mov_b32 v[134:135], v[132:133], v[130:131] op_sel:[1,0]
	v_mov_b32_e32 v133, v131
	v_pk_add_f32 v[130:131], v[134:135], v[132:133]
	v_mul_f32_e32 v132, v24, v24
	v_mul_f32_e32 v133, v25, v25
	v_pk_add_f32 v[130:131], v[130:131], v[130:131] op_sel:[0,1] op_sel_hi:[1,0]
	v_mov_b32_e32 v129, v132
	v_mov_b32_e32 v131, v133
	v_pk_add_f32 v[128:129], v[128:129], v[130:131]
	v_mul_f32_e32 v130, v29, v29
	v_mul_f32_e32 v132, v31, v31
	v_mul_f32_e32 v134, v26, v26
	v_mul_f32_e32 v135, v27, v27
	v_pk_fma_f32 v[130:131], v[28:29], v[28:29], v[130:131] op_sel_hi:[1,1,0]
	v_pk_fma_f32 v[132:133], v[30:31], v[30:31], v[132:133] op_sel_hi:[1,1,0]
	v_mov_b32_e32 v131, v134
	v_mov_b32_e32 v133, v135
	v_pk_add_f32 v[130:131], v[130:131], v[132:133]
	v_pk_mul_f32 v[38:39], v[38:39], v[164:165] op_sel_hi:[1,0]
	v_pk_add_f32 v[128:129], v[128:129], v[130:131]
	v_pk_mul_f32 v[36:37], v[36:37], v[164:165] op_sel_hi:[1,0]
	v_add_f32_e32 v128, v128, v129
	s_waitcnt lgkmcnt(0)
	s_nop 1
	v_add_f32_dpp v128, v128, v128 quad_perm:[1,0,3,2] row_mask:0xf bank_mask:0xf
	s_waitcnt lgkmcnt(0)
	s_nop 1
	v_add_f32_dpp v128, v128, v128 quad_perm:[2,3,0,1] row_mask:0xf bank_mask:0xf
	s_waitcnt lgkmcnt(0)
	s_nop 1
	v_add_f32_dpp v128, v128, v128 row_half_mirror row_mask:0xf bank_mask:0xf
	s_waitcnt lgkmcnt(0)
	s_nop 1
	v_add_f32_dpp v128, v128, v128 row_mirror row_mask:0xf bank_mask:0xf
	s_waitcnt lgkmcnt(0)
	v_mov_b32_e32 v129, v128
	s_nop 1
	v_permlane16_swap_b32_e32 v128, v129
	s_nop 0
	v_add_f32_e32 v128, v128, v129
	s_waitcnt lgkmcnt(0)
	v_mov_b32_e32 v129, v128
	s_nop 1
	v_permlane32_swap_b32_e32 v128, v129
	s_nop 0
	v_add_f32_e32 v128, v128, v129
	v_fmamk_f32 v128, v128, 0x3a000000, v232
	v_rsq_f32_e32 v166, v128
	global_load_dwordx4 v[132:135], v[136:137], off
	global_load_dwordx4 v[128:131], v[170:171], off
	global_load_dwordx4 v[180:183], v[168:169], off
	v_pk_mul_f32 v[34:35], v[34:35], v[166:167] op_sel_hi:[1,0]
	v_pk_mul_f32 v[32:33], v[32:33], v[166:167] op_sel_hi:[1,0]
	s_waitcnt vmcnt(2)
	v_pk_mul_f32 v[90:91], v[90:91], v[134:135]
	v_pk_mul_f32 v[88:89], v[88:89], v[132:133]
	s_waitcnt vmcnt(0)
	v_pk_add_f32 v[172:173], v[182:183], 1.0 op_sel_hi:[1,0]
	v_pk_add_f32 v[174:175], v[180:181], 1.0 op_sel_hi:[1,0]
	v_pk_fma_f32 v[90:91], v[90:91], v[172:173], v[130:131]
	v_pk_fma_f32 v[88:89], v[88:89], v[174:175], v[128:129]
	v_cvt_pk_bf16_f32 v181, v90, v91
	v_pk_mul_f32 v[90:91], v[102:103], v[162:163] op_sel_hi:[1,0]
	v_cvt_pk_bf16_f32 v180, v88, v89
	v_lshl_add_u64 v[88:89], s[8:9], 0, v[148:149]
	v_pk_mul_f32 v[100:101], v[100:101], v[132:133]
	v_pk_mul_f32 v[90:91], v[90:91], v[134:135]
	v_add_co_u32_e32 v88, vcc, s30, v88
	v_pk_fma_f32 v[90:91], v[90:91], v[172:173], v[130:131]
	v_pk_fma_f32 v[100:101], v[100:101], v[174:175], v[128:129]
	v_addc_co_u32_e32 v89, vcc, 0, v89, vcc
	v_cvt_pk_bf16_f32 v100, v100, v101
	v_cvt_pk_bf16_f32 v101, v90, v91
	v_lshl_add_u64 v[90:91], v[156:157], 0, s[16:17]
	global_store_dwordx2 v[88:89], v[180:181], off
	global_store_dwordx2 v[90:91], v[100:101], off
	v_pk_mul_f32 v[100:101], v[110:111], v[164:165] op_sel_hi:[1,0]
	v_pk_mul_f32 v[102:103], v[108:109], v[164:165] op_sel_hi:[1,0]
	v_pk_mul_f32 v[100:101], v[134:135], v[100:101]
	v_pk_mul_f32 v[102:103], v[132:133], v[102:103]
	v_pk_fma_f32 v[100:101], v[100:101], v[172:173], v[130:131]
	v_pk_fma_f32 v[102:103], v[102:103], v[174:175], v[128:129]
	v_pk_mul_f32 v[108:109], v[124:125], v[166:167] op_sel_hi:[1,0]
	v_cvt_pk_bf16_f32 v102, v102, v103
	v_cvt_pk_bf16_f32 v103, v100, v101
	v_lshl_add_u64 v[100:101], v[156:157], 0, s[18:19]
	global_store_dwordx2 v[100:101], v[102:103], off
	v_pk_mul_f32 v[102:103], v[126:127], v[166:167] op_sel_hi:[1,0]
	v_pk_mul_f32 v[108:109], v[132:133], v[108:109]
	v_pk_mul_f32 v[102:103], v[134:135], v[102:103]
	v_pk_fma_f32 v[108:109], v[174:175], v[108:109], v[128:129]
	v_pk_fma_f32 v[102:103], v[172:173], v[102:103], v[130:131]
	v_cvt_pk_bf16_f32 v108, v108, v109
	v_cvt_pk_bf16_f32 v109, v102, v103
	v_lshl_add_u64 v[102:103], v[156:157], 0, s[22:23]
	global_store_dwordx2 v[102:103], v[108:109], off
	global_load_dwordx4 v[108:111], v[136:137], off offset:1024
	s_nop 0
	global_load_dwordx4 v[124:127], v[170:171], off offset:1024
	global_load_dwordx4 v[128:131], v[168:169], off offset:1024
	s_cselect_b64 s[16:17], -1, 0
	s_add_u32 s8, s8, s10
	s_addc_u32 s9, s9, s11
	s_add_u32 s12, s12, s10
	s_addc_u32 s13, s13, s11
	s_waitcnt vmcnt(2)
	v_pk_mul_f32 v[72:73], v[72:73], v[108:109]
	v_pk_mul_f32 v[74:75], v[74:75], v[110:111]
	s_waitcnt vmcnt(0)
	v_pk_add_f32 v[130:131], v[130:131], 1.0 op_sel_hi:[1,0]
	v_pk_add_f32 v[128:129], v[128:129], 1.0 op_sel_hi:[1,0]
	v_pk_fma_f32 v[74:75], v[74:75], v[130:131], v[126:127]
	v_pk_fma_f32 v[72:73], v[72:73], v[128:129], v[124:125]
	s_nop 0
	v_cvt_pk_bf16_f32 v72, v72, v73
	v_cvt_pk_bf16_f32 v73, v74, v75
	global_store_dwordx2 v[88:89], v[72:73], off offset:512
	v_pk_mul_f32 v[72:73], v[86:87], v[162:163] op_sel_hi:[1,0]
	v_pk_mul_f32 v[74:75], v[84:85], v[162:163] op_sel_hi:[1,0]
	v_pk_mul_f32 v[72:73], v[72:73], v[110:111]
	v_pk_mul_f32 v[74:75], v[74:75], v[108:109]
	v_pk_fma_f32 v[72:73], v[72:73], v[130:131], v[126:127]
	v_pk_fma_f32 v[74:75], v[74:75], v[128:129], v[124:125]
	s_nop 0
	v_cvt_pk_bf16_f32 v74, v74, v75
	v_cvt_pk_bf16_f32 v75, v72, v73
	global_store_dwordx2 v[90:91], v[74:75], off offset:512
	v_pk_mul_f32 v[72:73], v[106:107], v[164:165] op_sel_hi:[1,0]
	v_pk_mul_f32 v[74:75], v[104:105], v[164:165] op_sel_hi:[1,0]
	v_pk_mul_f32 v[72:73], v[72:73], v[110:111]
	v_pk_mul_f32 v[74:75], v[74:75], v[108:109]
	v_pk_fma_f32 v[72:73], v[72:73], v[130:131], v[126:127]
	v_pk_fma_f32 v[74:75], v[74:75], v[128:129], v[124:125]
	s_nop 0
	v_cvt_pk_bf16_f32 v74, v74, v75
	v_cvt_pk_bf16_f32 v75, v72, v73
	global_store_dwordx2 v[100:101], v[74:75], off offset:512
	v_pk_mul_f32 v[72:73], v[122:123], v[166:167] op_sel_hi:[1,0]
	v_pk_mul_f32 v[74:75], v[120:121], v[166:167] op_sel_hi:[1,0]
	v_pk_mul_f32 v[72:73], v[110:111], v[72:73]
	v_pk_mul_f32 v[74:75], v[108:109], v[74:75]
	v_pk_fma_f32 v[72:73], v[72:73], v[130:131], v[126:127]
	v_pk_fma_f32 v[74:75], v[74:75], v[128:129], v[124:125]
	s_nop 0
	v_cvt_pk_bf16_f32 v74, v74, v75
	v_cvt_pk_bf16_f32 v75, v72, v73
	global_store_dwordx2 v[102:103], v[74:75], off offset:512
	global_load_dwordx4 v[72:75], v[136:137], off offset:2048
	s_nop 0
	global_load_dwordx4 v[84:87], v[170:171], off offset:2048
	global_load_dwordx4 v[104:107], v[168:169], off offset:2048
	s_waitcnt vmcnt(2)
	v_pk_mul_f32 v[68:69], v[68:69], v[72:73]
	v_pk_mul_f32 v[70:71], v[70:71], v[74:75]
	s_waitcnt vmcnt(0)
	v_pk_add_f32 v[106:107], v[106:107], 1.0 op_sel_hi:[1,0]
	v_pk_add_f32 v[104:105], v[104:105], 1.0 op_sel_hi:[1,0]
	v_pk_fma_f32 v[70:71], v[70:71], v[106:107], v[86:87]
	v_pk_fma_f32 v[68:69], v[68:69], v[104:105], v[84:85]
	s_nop 0
	v_cvt_pk_bf16_f32 v68, v68, v69
	v_cvt_pk_bf16_f32 v69, v70, v71
	global_store_dwordx2 v[88:89], v[68:69], off offset:1024
	v_pk_mul_f32 v[68:69], v[82:83], v[162:163] op_sel_hi:[1,0]
	v_pk_mul_f32 v[70:71], v[80:81], v[162:163] op_sel_hi:[1,0]
	v_pk_mul_f32 v[68:69], v[68:69], v[74:75]
	v_pk_mul_f32 v[70:71], v[70:71], v[72:73]
	v_pk_fma_f32 v[68:69], v[68:69], v[106:107], v[86:87]
	v_pk_fma_f32 v[70:71], v[70:71], v[104:105], v[84:85]
	s_nop 0
	v_cvt_pk_bf16_f32 v70, v70, v71
	v_cvt_pk_bf16_f32 v71, v68, v69
	global_store_dwordx2 v[90:91], v[70:71], off offset:1024
	v_pk_mul_f32 v[68:69], v[98:99], v[164:165] op_sel_hi:[1,0]
	v_pk_mul_f32 v[70:71], v[96:97], v[164:165] op_sel_hi:[1,0]
	v_pk_mul_f32 v[68:69], v[68:69], v[74:75]
	v_pk_mul_f32 v[70:71], v[70:71], v[72:73]
	v_pk_fma_f32 v[68:69], v[68:69], v[106:107], v[86:87]
	v_pk_fma_f32 v[70:71], v[70:71], v[104:105], v[84:85]
	s_nop 0
	v_cvt_pk_bf16_f32 v70, v70, v71
	v_cvt_pk_bf16_f32 v71, v68, v69
	global_store_dwordx2 v[100:101], v[70:71], off offset:1024
	v_pk_mul_f32 v[68:69], v[118:119], v[166:167] op_sel_hi:[1,0]
	v_pk_mul_f32 v[70:71], v[116:117], v[166:167] op_sel_hi:[1,0]
	v_pk_mul_f32 v[68:69], v[68:69], v[74:75]
	v_pk_mul_f32 v[70:71], v[70:71], v[72:73]
	v_pk_fma_f32 v[68:69], v[68:69], v[106:107], v[86:87]
	v_pk_fma_f32 v[70:71], v[70:71], v[104:105], v[84:85]
	s_nop 0
	v_cvt_pk_bf16_f32 v70, v70, v71
	v_cvt_pk_bf16_f32 v71, v68, v69
	global_store_dwordx2 v[102:103], v[70:71], off offset:1024
	global_load_dwordx4 v[68:71], v[136:137], off offset:3072
	s_nop 0
	global_load_dwordx4 v[72:75], v[170:171], off offset:3072
	global_load_dwordx4 v[80:83], v[168:169], off offset:3072
	s_waitcnt vmcnt(2)
	v_pk_mul_f32 v[64:65], v[64:65], v[68:69]
	v_pk_mul_f32 v[66:67], v[66:67], v[70:71]
	s_waitcnt vmcnt(0)
	v_pk_add_f32 v[82:83], v[82:83], 1.0 op_sel_hi:[1,0]
	v_pk_add_f32 v[80:81], v[80:81], 1.0 op_sel_hi:[1,0]
	v_pk_fma_f32 v[66:67], v[66:67], v[82:83], v[74:75]
	v_pk_fma_f32 v[64:65], v[64:65], v[80:81], v[72:73]
	s_nop 0
	v_cvt_pk_bf16_f32 v64, v64, v65
	v_cvt_pk_bf16_f32 v65, v66, v67
	global_store_dwordx2 v[88:89], v[64:65], off offset:1536
	v_pk_mul_f32 v[64:65], v[78:79], v[162:163] op_sel_hi:[1,0]
	v_pk_mul_f32 v[66:67], v[76:77], v[162:163] op_sel_hi:[1,0]
	v_pk_mul_f32 v[64:65], v[64:65], v[70:71]
	v_pk_mul_f32 v[66:67], v[66:67], v[68:69]
	v_pk_fma_f32 v[64:65], v[64:65], v[82:83], v[74:75]
	v_pk_fma_f32 v[66:67], v[66:67], v[80:81], v[72:73]
	s_nop 0
	v_cvt_pk_bf16_f32 v66, v66, v67
	v_cvt_pk_bf16_f32 v67, v64, v65
	global_store_dwordx2 v[90:91], v[66:67], off offset:1536
	v_pk_mul_f32 v[64:65], v[94:95], v[164:165] op_sel_hi:[1,0]
	v_pk_mul_f32 v[66:67], v[92:93], v[164:165] op_sel_hi:[1,0]
	v_pk_mul_f32 v[64:65], v[64:65], v[70:71]
	v_pk_mul_f32 v[66:67], v[66:67], v[68:69]
	v_pk_fma_f32 v[64:65], v[64:65], v[82:83], v[74:75]
	v_pk_fma_f32 v[66:67], v[66:67], v[80:81], v[72:73]
	s_nop 0
	v_cvt_pk_bf16_f32 v66, v66, v67
	v_cvt_pk_bf16_f32 v67, v64, v65
	global_store_dwordx2 v[100:101], v[66:67], off offset:1536
	v_pk_mul_f32 v[66:67], v[112:113], v[166:167] op_sel_hi:[1,0]
	v_pk_mul_f32 v[64:65], v[114:115], v[166:167] op_sel_hi:[1,0]
	v_pk_mul_f32 v[66:67], v[66:67], v[68:69]
	v_pk_mul_f32 v[64:65], v[64:65], v[70:71]
	v_pk_fma_f32 v[66:67], v[66:67], v[80:81], v[72:73]
	v_add_co_u32_e32 v72, vcc, s77, v170
	v_pk_fma_f32 v[64:65], v[64:65], v[82:83], v[74:75]
	s_nop 0
	v_addc_co_u32_e32 v73, vcc, 0, v171, vcc
	v_cvt_pk_bf16_f32 v66, v66, v67
	v_cvt_pk_bf16_f32 v67, v64, v65
	v_add_co_u32_e32 v74, vcc, s77, v168
	global_store_dwordx2 v[102:103], v[66:67], off offset:1536
	s_nop 0
	v_addc_co_u32_e32 v75, vcc, 0, v169, vcc
	global_load_dwordx4 v[64:67], v[138:139], off
	global_load_dwordx4 v[78:81], v[74:75], off
	global_load_dwordx4 v[68:71], v[72:73], off
	v_subrev_co_u32_e32 v178, vcc, 1, v178
	s_waitcnt vmcnt(2)
	v_pk_mul_f32 v[48:49], v[48:49], v[64:65]
	s_waitcnt vmcnt(1)
	v_pk_add_f32 v[76:77], v[80:81], 1.0 op_sel_hi:[1,0]
	v_pk_add_f32 v[78:79], v[78:79], 1.0 op_sel_hi:[1,0]
	v_pk_mul_f32 v[50:51], v[50:51], v[66:67]
	s_waitcnt vmcnt(0)
	v_pk_fma_f32 v[48:49], v[48:49], v[78:79], v[68:69]
	v_pk_fma_f32 v[50:51], v[50:51], v[76:77], v[70:71]
	v_cvt_pk_bf16_f32 v48, v48, v49
	v_cvt_pk_bf16_f32 v49, v50, v51
	global_store_dwordx2 v[88:89], v[48:49], off offset:2048
	v_pk_mul_f32 v[48:49], v[54:55], v[162:163] op_sel_hi:[1,0]
	v_pk_mul_f32 v[50:51], v[52:53], v[162:163] op_sel_hi:[1,0]
	v_pk_mul_f32 v[48:49], v[48:49], v[66:67]
	v_pk_mul_f32 v[50:51], v[50:51], v[64:65]
	v_pk_fma_f32 v[48:49], v[48:49], v[76:77], v[70:71]
	v_pk_fma_f32 v[50:51], v[50:51], v[78:79], v[68:69]
	s_nop 0
	v_cvt_pk_bf16_f32 v50, v50, v51
	v_cvt_pk_bf16_f32 v51, v48, v49
	global_store_dwordx2 v[90:91], v[50:51], off offset:2048
	v_pk_mul_f32 v[48:49], v[58:59], v[164:165] op_sel_hi:[1,0]
	v_pk_mul_f32 v[50:51], v[56:57], v[164:165] op_sel_hi:[1,0]
	v_pk_mul_f32 v[48:49], v[48:49], v[66:67]
	v_pk_mul_f32 v[50:51], v[50:51], v[64:65]
	v_pk_fma_f32 v[48:49], v[48:49], v[76:77], v[70:71]
	v_pk_fma_f32 v[50:51], v[50:51], v[78:79], v[68:69]
	s_nop 0
	v_cvt_pk_bf16_f32 v50, v50, v51
	v_cvt_pk_bf16_f32 v51, v48, v49
	global_store_dwordx2 v[100:101], v[50:51], off offset:2048
	v_pk_mul_f32 v[48:49], v[62:63], v[166:167] op_sel_hi:[1,0]
	v_pk_mul_f32 v[50:51], v[60:61], v[166:167] op_sel_hi:[1,0]
	v_pk_mul_f32 v[48:49], v[48:49], v[66:67]
	v_pk_mul_f32 v[50:51], v[50:51], v[64:65]
	v_pk_fma_f32 v[48:49], v[48:49], v[76:77], v[70:71]
	v_pk_fma_f32 v[50:51], v[50:51], v[78:79], v[68:69]
	s_nop 0
	v_cvt_pk_bf16_f32 v50, v50, v51
	v_cvt_pk_bf16_f32 v51, v48, v49
	global_store_dwordx2 v[102:103], v[50:51], off offset:2048
	global_load_dwordx4 v[52:55], v[140:141], off
	s_nop 0
	global_load_dwordx4 v[48:51], v[72:73], off offset:1024
	global_load_dwordx4 v[58:61], v[74:75], off offset:1024
	s_waitcnt vmcnt(2)
	v_pk_mul_f32 v[44:45], v[44:45], v[52:53]
	v_pk_mul_f32 v[46:47], v[46:47], v[54:55]
	s_waitcnt vmcnt(0)
	v_pk_add_f32 v[56:57], v[60:61], 1.0 op_sel_hi:[1,0]
	v_pk_add_f32 v[58:59], v[58:59], 1.0 op_sel_hi:[1,0]
	v_pk_mul_f32 v[40:41], v[40:41], v[52:53]
	v_pk_mul_f32 v[42:43], v[42:43], v[54:55]
	v_pk_mul_f32 v[36:37], v[36:37], v[52:53]
	v_pk_mul_f32 v[38:39], v[38:39], v[54:55]
	v_pk_mul_f32 v[32:33], v[32:33], v[52:53]
	v_pk_mul_f32 v[34:35], v[34:35], v[54:55]
	v_pk_fma_f32 v[46:47], v[46:47], v[56:57], v[50:51]
	v_pk_fma_f32 v[44:45], v[44:45], v[58:59], v[48:49]
	v_pk_fma_f32 v[42:43], v[42:43], v[56:57], v[50:51]
	v_pk_fma_f32 v[40:41], v[40:41], v[58:59], v[48:49]
	v_pk_fma_f32 v[38:39], v[38:39], v[56:57], v[50:51]
	v_pk_fma_f32 v[36:37], v[36:37], v[58:59], v[48:49]
	v_pk_fma_f32 v[34:35], v[34:35], v[56:57], v[50:51]
	v_pk_fma_f32 v[32:33], v[32:33], v[58:59], v[48:49]
	v_cvt_pk_bf16_f32 v44, v44, v45
	v_cvt_pk_bf16_f32 v45, v46, v47
	v_cvt_pk_bf16_f32 v40, v40, v41
	v_cvt_pk_bf16_f32 v41, v42, v43
	v_cvt_pk_bf16_f32 v36, v36, v37
	v_cvt_pk_bf16_f32 v37, v38, v39
	v_cvt_pk_bf16_f32 v32, v32, v33
	v_cvt_pk_bf16_f32 v33, v34, v35
	global_store_dwordx2 v[88:89], v[44:45], off offset:2560
	global_store_dwordx2 v[90:91], v[40:41], off offset:2560
	global_store_dwordx2 v[100:101], v[36:37], off offset:2560
	global_store_dwordx2 v[102:103], v[32:33], off offset:2560
	global_load_dwordx4 v[32:35], v[142:143], off
	s_nop 0
	global_load_dwordx4 v[36:39], v[72:73], off offset:2048
	global_load_dwordx4 v[40:43], v[74:75], off offset:2048
	s_waitcnt vmcnt(2)
	v_pk_mul_f32 v[8:9], v[8:9], v[32:33]
	v_pk_mul_f32 v[10:11], v[10:11], v[34:35]
	s_waitcnt vmcnt(0)
	v_pk_add_f32 v[42:43], v[42:43], 1.0 op_sel_hi:[1,0]
	v_pk_add_f32 v[40:41], v[40:41], 1.0 op_sel_hi:[1,0]
	v_pk_fma_f32 v[10:11], v[10:11], v[42:43], v[38:39]
	v_pk_fma_f32 v[8:9], v[8:9], v[40:41], v[36:37]
	s_nop 0
	v_cvt_pk_bf16_f32 v8, v8, v9
	v_cvt_pk_bf16_f32 v9, v10, v11
	global_store_dwordx2 v[88:89], v[8:9], off offset:3072
	v_pk_mul_f32 v[8:9], v[14:15], v[162:163] op_sel_hi:[1,0]
	v_pk_mul_f32 v[10:11], v[12:13], v[162:163] op_sel_hi:[1,0]
	v_pk_mul_f32 v[8:9], v[8:9], v[34:35]
	v_pk_mul_f32 v[10:11], v[10:11], v[32:33]
	v_pk_fma_f32 v[8:9], v[8:9], v[42:43], v[38:39]
	v_pk_fma_f32 v[10:11], v[10:11], v[40:41], v[36:37]
	s_nop 0
	v_cvt_pk_bf16_f32 v10, v10, v11
	v_cvt_pk_bf16_f32 v11, v8, v9
	global_store_dwordx2 v[90:91], v[10:11], off offset:3072
	v_pk_mul_f32 v[8:9], v[22:23], v[164:165] op_sel_hi:[1,0]
	v_pk_mul_f32 v[10:11], v[20:21], v[164:165] op_sel_hi:[1,0]
	v_pk_mul_f32 v[8:9], v[8:9], v[34:35]
	v_pk_mul_f32 v[10:11], v[10:11], v[32:33]
	v_pk_fma_f32 v[8:9], v[8:9], v[42:43], v[38:39]
	v_pk_fma_f32 v[10:11], v[10:11], v[40:41], v[36:37]
	s_nop 0
	v_cvt_pk_bf16_f32 v10, v10, v11
	v_cvt_pk_bf16_f32 v11, v8, v9
	global_store_dwordx2 v[100:101], v[10:11], off offset:3072
	v_pk_mul_f32 v[8:9], v[30:31], v[166:167] op_sel_hi:[1,0]
	v_pk_mul_f32 v[10:11], v[28:29], v[166:167] op_sel_hi:[1,0]
	v_pk_mul_f32 v[8:9], v[8:9], v[34:35]
	v_pk_mul_f32 v[10:11], v[10:11], v[32:33]
	v_pk_fma_f32 v[8:9], v[8:9], v[42:43], v[38:39]
	v_pk_fma_f32 v[10:11], v[10:11], v[40:41], v[36:37]
	s_nop 0
	v_cvt_pk_bf16_f32 v10, v10, v11
	v_cvt_pk_bf16_f32 v11, v8, v9
	global_store_dwordx2 v[102:103], v[10:11], off offset:3072
	global_load_dwordx4 v[8:11], v[144:145], off
	s_nop 0
	global_load_dwordx4 v[12:15], v[72:73], off offset:3072
	global_load_dwordx4 v[20:23], v[74:75], off offset:3072
	s_waitcnt vmcnt(2)
	v_pk_mul_f32 v[0:1], v[0:1], v[8:9]
	v_pk_mul_f32 v[2:3], v[2:3], v[10:11]
	s_waitcnt vmcnt(0)
	v_pk_add_f32 v[22:23], v[22:23], 1.0 op_sel_hi:[1,0]
	v_pk_add_f32 v[20:21], v[20:21], 1.0 op_sel_hi:[1,0]
	v_pk_fma_f32 v[2:3], v[2:3], v[22:23], v[14:15]
	v_pk_fma_f32 v[0:1], v[0:1], v[20:21], v[12:13]
	s_nop 0
	v_cvt_pk_bf16_f32 v0, v0, v1
	v_cvt_pk_bf16_f32 v1, v2, v3
	global_store_dwordx2 v[88:89], v[0:1], off offset:3584
	v_pk_mul_f32 v[0:1], v[6:7], v[162:163] op_sel_hi:[1,0]
	v_pk_mul_f32 v[2:3], v[4:5], v[162:163] op_sel_hi:[1,0]
	v_pk_mul_f32 v[0:1], v[0:1], v[10:11]
	v_pk_mul_f32 v[2:3], v[2:3], v[8:9]
	v_pk_fma_f32 v[0:1], v[0:1], v[22:23], v[14:15]
	v_pk_fma_f32 v[2:3], v[2:3], v[20:21], v[12:13]
	s_nop 0
	v_cvt_pk_bf16_f32 v2, v2, v3
	v_cvt_pk_bf16_f32 v3, v0, v1
	global_store_dwordx2 v[90:91], v[2:3], off offset:3584
	v_pk_mul_f32 v[0:1], v[18:19], v[164:165] op_sel_hi:[1,0]
	v_pk_mul_f32 v[2:3], v[16:17], v[164:165] op_sel_hi:[1,0]
	v_pk_mul_f32 v[0:1], v[0:1], v[10:11]
	v_pk_mul_f32 v[2:3], v[2:3], v[8:9]
	v_pk_fma_f32 v[0:1], v[0:1], v[22:23], v[14:15]
	v_pk_fma_f32 v[2:3], v[2:3], v[20:21], v[12:13]
	s_nop 0
	v_cvt_pk_bf16_f32 v2, v2, v3
	v_cvt_pk_bf16_f32 v3, v0, v1
	global_store_dwordx2 v[100:101], v[2:3], off offset:3584
	v_pk_mul_f32 v[0:1], v[26:27], v[166:167] op_sel_hi:[1,0]
	v_pk_mul_f32 v[2:3], v[24:25], v[166:167] op_sel_hi:[1,0]
	v_pk_mul_f32 v[0:1], v[0:1], v[10:11]
	v_pk_mul_f32 v[2:3], v[2:3], v[8:9]
	v_pk_fma_f32 v[0:1], v[0:1], v[22:23], v[14:15]
	v_pk_fma_f32 v[2:3], v[2:3], v[20:21], v[12:13]
	s_nop 0
	v_cvt_pk_bf16_f32 v2, v2, v3
	v_cvt_pk_bf16_f32 v3, v0, v1
	v_cndmask_b32_e64 v0, 0, 1, vcc
	v_cndmask_b32_e64 v1, 0, 1, s[16:17]
	v_cndmask_b32_e64 v0, v1, v0, s[2:3]
	v_and_b32_e32 v0, 1, v0
	v_cmp_eq_u32_e32 vcc, 0, v0
	global_store_dwordx2 v[102:103], v[2:3], off offset:3584
	s_cbranch_vccz .LBB0_267

.LBB0_2205:
	s_nop 0
	v_lshl_add_u64 v[18:19], s[10:11], 0, v[12:13]
	v_add_co_u32_e32 v18, vcc, 0x3000000, v18
	global_load_dwordx4 v[86:89], v[2:3], off
	s_nop 0
	v_addc_co_u32_e32 v19, vcc, 0, v19, vcc
	global_load_dwordx2 v[54:55], v[18:19], off
	global_load_dwordx2 v[56:57], v[18:19], off offset:512
	global_load_dwordx2 v[70:71], v[18:19], off offset:1024
	global_load_dwordx2 v[72:73], v[18:19], off offset:1536
	global_load_dwordx2 v[90:91], v[18:19], off offset:2048
	global_load_dwordx2 v[92:93], v[18:19], off offset:2560
	global_load_dwordx2 v[94:95], v[18:19], off offset:3072
	global_load_dwordx2 v[96:97], v[18:19], off offset:3584
	s_add_i32 s20, s4, 2
	s_add_i32 s18, s4, 3
	v_lshl_add_u64 v[20:21], s[16:17], 0, v[12:13]
	s_ashr_i32 s21, s20, 31
	s_ashr_i32 s19, s18, 31
	v_add_co_u32_e32 v20, vcc, 0x3000000, v20
	s_lshl_b64 s[24:25], s[20:21], 12
	s_lshl_b64 s[26:27], s[18:19], 12
	v_addc_co_u32_e32 v21, vcc, 0, v21, vcc
	v_lshl_add_u64 v[98:99], v[14:15], 0, s[24:25]
	v_lshl_add_u64 v[100:101], v[14:15], 0, s[26:27]
	global_load_dwordx2 v[68:69], v[20:21], off
	global_load_dwordx2 v[66:67], v[20:21], off offset:512
	global_load_dwordx2 v[64:65], v[20:21], off offset:1024
	global_load_dwordx2 v[62:63], v[20:21], off offset:1536
	global_load_dwordx2 v[60:61], v[20:21], off offset:2048
	global_load_dwordx2 v[58:59], v[20:21], off offset:2560
	global_load_dwordx2 v[50:51], v[20:21], off offset:3072
	global_load_dwordx2 v[52:53], v[20:21], off offset:3584
	global_load_dwordx2 v[48:49], v[98:99], off
	global_load_dwordx2 v[46:47], v[98:99], off offset:512
	global_load_dwordx2 v[44:45], v[98:99], off offset:1024
	global_load_dwordx2 v[42:43], v[98:99], off offset:1536
	global_load_dwordx2 v[40:41], v[98:99], off offset:2048
	global_load_dwordx2 v[38:39], v[98:99], off offset:2560
	global_load_dwordx2 v[36:37], v[98:99], off offset:3072
	global_load_dwordx2 v[34:35], v[98:99], off offset:3584
	global_load_dwordx2 v[32:33], v[100:101], off
	global_load_dwordx2 v[30:31], v[100:101], off offset:512
	global_load_dwordx2 v[28:29], v[100:101], off offset:1024
	global_load_dwordx2 v[26:27], v[100:101], off offset:1536
	global_load_dwordx2 v[24:25], v[100:101], off offset:2048
	global_load_dwordx2 v[22:23], v[100:101], off offset:2560
	global_load_dwordx2 v[20:21], v[100:101], off offset:3072
	global_load_dwordx2 v[18:19], v[100:101], off offset:3584
	v_lshl_add_u64 v[76:77], s[6:7], 0, v[0:1]
	s_lshl_b64 s[20:21], s[20:21], 13
	s_lshl_b64 s[18:19], s[18:19], 13
	s_add_i32 s4, s4, s0
	s_cmp_lt_i32 s4, s22
	s_waitcnt vmcnt(31)
	v_cvt_f32_f16_sdwa v99, v55 dst_sel:DWORD dst_unused:UNUSED_PAD src0_sel:WORD_1
	v_cvt_f32_f16_sdwa v101, v54 dst_sel:DWORD dst_unused:UNUSED_PAD src0_sel:WORD_1
	s_waitcnt vmcnt(30)
	v_cvt_f32_f16_sdwa v103, v57 dst_sel:DWORD dst_unused:UNUSED_PAD src0_sel:WORD_1
	v_cvt_f32_f16_sdwa v105, v56 dst_sel:DWORD dst_unused:UNUSED_PAD src0_sel:WORD_1
	v_cvt_f32_f16_e32 v98, v55
	v_cvt_f32_f16_e32 v100, v54
	v_cvt_f32_f16_e32 v102, v57
	v_cvt_f32_f16_e32 v104, v56
	s_waitcnt vmcnt(29)
	v_cvt_f32_f16_e32 v106, v70
	v_cvt_f32_f16_sdwa v107, v70 dst_sel:DWORD dst_unused:UNUSED_PAD src0_sel:WORD_1
	v_cvt_f32_f16_e32 v108, v71
	v_cvt_f32_f16_sdwa v109, v71 dst_sel:DWORD dst_unused:UNUSED_PAD src0_sel:WORD_1
	s_waitcnt vmcnt(28)
	v_cvt_f32_f16_sdwa v111, v72 dst_sel:DWORD dst_unused:UNUSED_PAD src0_sel:WORD_1
	v_cvt_f32_f16_sdwa v113, v73 dst_sel:DWORD dst_unused:UNUSED_PAD src0_sel:WORD_1
	v_cvt_f32_f16_e32 v110, v72
	v_cvt_f32_f16_e32 v112, v73
	s_waitcnt vmcnt(27)
	v_cvt_f32_f16_sdwa v115, v91 dst_sel:DWORD dst_unused:UNUSED_PAD src0_sel:WORD_1
	v_cvt_f32_f16_e32 v114, v91
	v_cvt_f32_f16_sdwa v91, v90 dst_sel:DWORD dst_unused:UNUSED_PAD src0_sel:WORD_1
	v_cvt_f32_f16_e32 v90, v90
	s_waitcnt vmcnt(24)
	v_cvt_f32_f16_sdwa v55, v97 dst_sel:DWORD dst_unused:UNUSED_PAD src0_sel:WORD_1
	v_cvt_f32_f16_e32 v54, v97
	v_cvt_f32_f16_sdwa v57, v96 dst_sel:DWORD dst_unused:UNUSED_PAD src0_sel:WORD_1
	v_cvt_f32_f16_e32 v56, v96
	v_mov_b32_e32 v96, v101
	v_mov_b32_e32 v97, v105
	v_mov_b32_e32 v120, v99
	v_mov_b32_e32 v121, v103
	v_cvt_f32_f16_e32 v116, v92
	v_cvt_f32_f16_sdwa v117, v92 dst_sel:DWORD dst_unused:UNUSED_PAD src0_sel:WORD_1
	v_cvt_f32_f16_e32 v92, v93
	v_cvt_f32_f16_sdwa v93, v93 dst_sel:DWORD dst_unused:UNUSED_PAD src0_sel:WORD_1
	v_cvt_f32_f16_e32 v70, v94
	v_cvt_f32_f16_sdwa v71, v94 dst_sel:DWORD dst_unused:UNUSED_PAD src0_sel:WORD_1
	v_cvt_f32_f16_e32 v72, v95
	v_cvt_f32_f16_sdwa v73, v95 dst_sel:DWORD dst_unused:UNUSED_PAD src0_sel:WORD_1
	v_mov_b32_e32 v94, v100
	v_mov_b32_e32 v95, v104
	v_mov_b32_e32 v118, v98
	v_mov_b32_e32 v119, v102
	v_pk_mul_f32 v[122:123], v[108:109], v[108:109]
	v_pk_mul_f32 v[124:125], v[106:107], v[106:107]
	v_pk_mul_f32 v[96:97], v[96:97], v[96:97]
	v_pk_mul_f32 v[120:121], v[120:121], v[120:121]
	v_pk_mov_b32 v[136:137], v[124:125], v[122:123] op_sel:[1,0]
	v_mov_b32_e32 v125, v123
	v_pk_fma_f32 v[94:95], v[94:95], v[94:95], v[96:97]
	v_pk_fma_f32 v[96:97], v[118:119], v[118:119], v[120:121]
	v_mul_f32_e32 v74, v111, v111
	v_mul_f32_e32 v126, v113, v113
	v_pk_add_f32 v[118:119], v[136:137], v[124:125]
	v_pk_add_f32 v[94:95], v[94:95], v[96:97]
	v_mul_f32_e32 v85, v90, v90
	v_mul_f32_e32 v135, v91, v91
	v_mul_f32_e32 v140, v114, v114
	v_mul_f32_e32 v141, v115, v115
	v_pk_fma_f32 v[122:123], v[110:111], v[110:111], v[74:75] op_sel_hi:[1,1,0]
	v_pk_fma_f32 v[126:127], v[112:113], v[112:113], v[126:127] op_sel_hi:[1,1,0]
	v_pk_add_f32 v[96:97], v[118:119], v[118:119] op_sel:[0,1] op_sel_hi:[1,0]
	v_pk_add_f32 v[94:95], v[94:95], v[94:95] op_sel:[0,1] op_sel_hi:[1,0]
	v_pk_mul_f32 v[128:129], v[92:93], v[92:93]
	v_pk_mul_f32 v[130:131], v[116:117], v[116:117]
	v_mov_b32_e32 v123, v140
	v_mov_b32_e32 v127, v141
	v_mov_b32_e32 v97, v135
	v_mov_b32_e32 v95, v85
	v_pk_mov_b32 v[138:139], v[130:131], v[128:129] op_sel:[1,0]
	v_mov_b32_e32 v131, v129
	v_pk_add_f32 v[118:119], v[122:123], v[126:127]
	v_pk_add_f32 v[94:95], v[94:95], v[96:97]
	v_mul_f32_e32 v132, v71, v71
	v_mul_f32_e32 v134, v73, v73
	v_pk_add_f32 v[120:121], v[138:139], v[130:131]
	v_pk_add_f32 v[94:95], v[94:95], v[118:119]
	v_mul_f32_e32 v142, v56, v56
	v_mul_f32_e32 v143, v57, v57
	v_mul_f32_e32 v144, v54, v54
	v_mul_f32_e32 v145, v55, v55
	v_pk_fma_f32 v[128:129], v[70:71], v[70:71], v[132:133] op_sel_hi:[1,1,0]
	v_pk_fma_f32 v[132:133], v[72:73], v[72:73], v[134:135] op_sel_hi:[1,1,0]
	v_pk_add_f32 v[120:121], v[120:121], v[120:121] op_sel:[0,1] op_sel_hi:[1,0]
	v_pk_add_f32 v[94:95], v[94:95], v[94:95] op_sel:[0,1] op_sel_hi:[1,0]
	v_mov_b32_e32 v129, v144
	v_mov_b32_e32 v133, v145
	v_mov_b32_e32 v121, v143
	v_mov_b32_e32 v95, v142
	v_pk_add_f32 v[122:123], v[128:129], v[132:133]
	v_pk_add_f32 v[94:95], v[94:95], v[120:121]
	s_nop 0
	v_pk_add_f32 v[94:95], v[94:95], v[122:123]
	s_nop 0
	v_add_f32_e32 v74, v94, v95
	s_waitcnt lgkmcnt(0)
	s_nop 1
	v_add_f32_dpp v74, v74, v74 quad_perm:[1,0,3,2] row_mask:0xf bank_mask:0xf
	s_waitcnt lgkmcnt(0)
	s_nop 1
	v_add_f32_dpp v74, v74, v74 quad_perm:[2,3,0,1] row_mask:0xf bank_mask:0xf
	s_waitcnt lgkmcnt(0)
	s_nop 1
	v_add_f32_dpp v74, v74, v74 row_half_mirror row_mask:0xf bank_mask:0xf
	s_waitcnt lgkmcnt(0)
	s_nop 1
	v_add_f32_dpp v74, v74, v74 row_mirror row_mask:0xf bank_mask:0xf
	s_waitcnt lgkmcnt(0)
	v_mov_b32_e32 v85, v74
	s_nop 1
	v_permlane16_swap_b32_e32 v74, v85
	s_nop 0
	v_add_f32_e32 v74, v74, v85
	s_waitcnt lgkmcnt(0)
	v_mov_b32_e32 v85, v74
	s_nop 1
	v_permlane32_swap_b32_e32 v74, v85
	s_nop 0
	v_add_f32_e32 v74, v74, v85
	v_fmamk_f32 v74, v74, 0x3a000000, v84
	v_rsq_f32_e32 v74, v74
	s_nop 0
	v_pk_mul_f32 v[94:95], v[74:75], v[100:101] op_sel_hi:[0,1]
	v_pk_mul_f32 v[96:97], v[74:75], v[98:99] op_sel_hi:[0,1]
	v_pk_mul_f32 v[88:89], v[88:89], v[96:97]
	v_pk_mul_f32 v[86:87], v[86:87], v[94:95]
	global_store_dwordx4 v[76:77], v[86:89], off
	global_load_dwordx4 v[86:89], v[2:3], off offset:1024
	v_pk_mul_f32 v[94:95], v[74:75], v[102:103] op_sel_hi:[0,1]
	v_pk_mul_f32 v[96:97], v[74:75], v[104:105] op_sel_hi:[0,1]
	v_pk_mul_f32 v[90:91], v[74:75], v[90:91] op_sel_hi:[0,1]
	s_waitcnt vmcnt(23)
	v_cvt_f32_f16_e32 v98, v65
	v_cvt_f32_f16_sdwa v99, v65 dst_sel:DWORD dst_unused:UNUSED_PAD src0_sel:WORD_1
	s_waitcnt vmcnt(22)
	v_cvt_f32_f16_e32 v100, v62
	v_cvt_f32_f16_sdwa v101, v62 dst_sel:DWORD dst_unused:UNUSED_PAD src0_sel:WORD_1
	v_cvt_f32_f16_e32 v102, v63
	v_cvt_f32_f16_sdwa v103, v63 dst_sel:DWORD dst_unused:UNUSED_PAD src0_sel:WORD_1
	v_pk_mul_f32 v[62:63], v[74:75], v[70:71] op_sel_hi:[0,1]
	s_waitcnt vmcnt(21)
	v_cvt_f32_f16_sdwa v105, v61 dst_sel:DWORD dst_unused:UNUSED_PAD src0_sel:WORD_1
	v_cvt_f32_f16_e32 v104, v61
	s_waitcnt vmcnt(19)
	v_cvt_f32_f16_sdwa v61, v51 dst_sel:DWORD dst_unused:UNUSED_PAD src0_sel:WORD_1
	v_mul_f32_e32 v118, v103, v103
	v_mul_f32_e32 v131, v105, v105
	v_mul_f32_e32 v130, v104, v104
	v_mul_f32_e32 v126, v61, v61
	s_waitcnt vmcnt(0)
	v_pk_mul_f32 v[86:87], v[86:87], v[96:97]
	v_pk_mul_f32 v[88:89], v[88:89], v[94:95]
	global_store_dwordx4 v[76:77], v[86:89], off offset:1024
	global_load_dwordx4 v[86:89], v[2:3], off offset:2048
	v_pk_mul_f32 v[94:95], v[74:75], v[108:109] op_sel_hi:[0,1]
	v_pk_mul_f32 v[96:97], v[74:75], v[106:107] op_sel_hi:[0,1]
	v_cvt_f32_f16_sdwa v107, v60 dst_sel:DWORD dst_unused:UNUSED_PAD src0_sel:WORD_1
	v_cvt_f32_f16_e32 v106, v60
	v_cvt_f32_f16_e32 v108, v58
	v_cvt_f32_f16_sdwa v109, v58 dst_sel:DWORD dst_unused:UNUSED_PAD src0_sel:WORD_1
	v_cvt_f32_f16_e32 v58, v50
	v_cvt_f32_f16_e32 v60, v51
	v_cvt_f32_f16_sdwa v51, v53 dst_sel:DWORD dst_unused:UNUSED_PAD src0_sel:WORD_1
	v_mul_f32_e32 v85, v106, v106
	v_mul_f32_e32 v127, v107, v107
	v_pk_mul_f32 v[122:123], v[108:109], v[108:109]
	v_mul_f32_e32 v135, v51, v51
	s_waitcnt vmcnt(0)
	v_pk_mul_f32 v[86:87], v[86:87], v[96:97]
	v_pk_mul_f32 v[88:89], v[88:89], v[94:95]
	global_store_dwordx4 v[76:77], v[86:89], off offset:2048
	global_load_dwordx4 v[86:89], v[2:3], off offset:3072
	v_pk_mul_f32 v[94:95], v[74:75], v[112:113] op_sel_hi:[0,1]
	v_pk_mul_f32 v[96:97], v[74:75], v[110:111] op_sel_hi:[0,1]
	v_pk_mul_f32 v[112:113], v[98:99], v[98:99]
	v_cvt_f32_f16_e32 v110, v59
	v_cvt_f32_f16_sdwa v111, v59 dst_sel:DWORD dst_unused:UNUSED_PAD src0_sel:WORD_1
	v_cvt_f32_f16_sdwa v59, v50 dst_sel:DWORD dst_unused:UNUSED_PAD src0_sel:WORD_1
	v_cvt_f32_f16_e32 v50, v53
	v_cvt_f32_f16_sdwa v53, v52 dst_sel:DWORD dst_unused:UNUSED_PAD src0_sel:WORD_1
	v_cvt_f32_f16_e32 v52, v52
	v_pk_mul_f32 v[120:121], v[110:111], v[110:111]
	v_mul_f32_e32 v124, v59, v59
	v_mul_f32_e32 v133, v53, v53
	v_mul_f32_e32 v132, v52, v52
	v_mul_f32_e32 v134, v50, v50
	s_waitcnt vmcnt(0)
	v_pk_mul_f32 v[86:87], v[86:87], v[96:97]
	v_pk_mul_f32 v[88:89], v[88:89], v[94:95]
	global_store_dwordx4 v[76:77], v[86:89], off offset:3072
	global_load_dwordx4 v[86:89], v[4:5], off
	v_add_co_u32_e32 v76, vcc, s1, v76
	v_pk_mul_f32 v[94:95], v[74:75], v[114:115] op_sel_hi:[0,1]
	s_nop 0
	v_addc_co_u32_e32 v77, vcc, 0, v77, vcc
	v_cvt_f32_f16_e32 v96, v66
	v_cvt_f32_f16_sdwa v97, v66 dst_sel:DWORD dst_unused:UNUSED_PAD src0_sel:WORD_1
	v_cvt_f32_f16_e32 v66, v64
	v_mov_b32_e32 v71, v96
	s_waitcnt vmcnt(0)
	v_pk_mul_f32 v[86:87], v[90:91], v[86:87]
	v_pk_mul_f32 v[88:89], v[94:95], v[88:89]
	global_store_dwordx4 v[76:77], v[86:89], off
	global_load_dwordx4 v[86:89], v[6:7], off
	v_pk_mul_f32 v[90:91], v[74:75], v[92:93] op_sel_hi:[0,1]
	v_pk_mul_f32 v[92:93], v[74:75], v[116:117] op_sel_hi:[0,1]
	v_cvt_f32_f16_e32 v94, v68
	v_cvt_f32_f16_sdwa v95, v68 dst_sel:DWORD dst_unused:UNUSED_PAD src0_sel:WORD_1
	v_cvt_f32_f16_e32 v68, v67
	v_mul_f32_e32 v116, v101, v101
	v_mov_b32_e32 v70, v94
	s_waitcnt vmcnt(0)
	v_pk_mul_f32 v[86:87], v[92:93], v[86:87]
	v_pk_mul_f32 v[88:89], v[90:91], v[88:89]
	global_store_dwordx4 v[76:77], v[86:89], off offset:1024
	global_load_dwordx4 v[86:89], v[8:9], off
	v_cvt_f32_f16_e32 v92, v69
	v_cvt_f32_f16_sdwa v93, v69 dst_sel:DWORD dst_unused:UNUSED_PAD src0_sel:WORD_1
	v_cvt_f32_f16_sdwa v69, v67 dst_sel:DWORD dst_unused:UNUSED_PAD src0_sel:WORD_1
	v_cvt_f32_f16_sdwa v67, v64 dst_sel:DWORD dst_unused:UNUSED_PAD src0_sel:WORD_1
	v_pk_mul_f32 v[64:65], v[74:75], v[72:73] op_sel_hi:[0,1]
	v_mov_b32_e32 v72, v95
	v_mov_b32_e32 v73, v97
	v_pk_mul_f32 v[114:115], v[66:67], v[66:67]
	v_pk_mul_f32 v[72:73], v[72:73], v[72:73]
	v_pk_mov_b32 v[128:129], v[114:115], v[112:113] op_sel:[1,0]
	v_mov_b32_e32 v115, v113
	v_pk_fma_f32 v[70:71], v[70:71], v[70:71], v[72:73]
	v_pk_fma_f32 v[112:113], v[100:101], v[100:101], v[116:117] op_sel_hi:[1,1,0]
	v_pk_fma_f32 v[116:117], v[102:103], v[102:103], v[118:119] op_sel_hi:[1,1,0]
	v_mov_b32_e32 v113, v130
	v_mov_b32_e32 v117, v131
	v_pk_mov_b32 v[118:119], v[122:123], v[120:121] op_sel:[1,0]
	v_mov_b32_e32 v123, v121
	v_pk_fma_f32 v[120:121], v[58:59], v[58:59], v[124:125] op_sel_hi:[1,1,0]
	v_pk_fma_f32 v[124:125], v[60:61], v[60:61], v[126:127] op_sel_hi:[1,1,0]
	v_mov_b32_e32 v121, v134
	v_mov_b32_e32 v125, v135
	v_lshl_add_u64 v[90:91], s[14:15], 0, v[0:1]
	s_waitcnt vmcnt(0)
	v_pk_mul_f32 v[62:63], v[62:63], v[86:87]
	v_pk_mul_f32 v[64:65], v[64:65], v[88:89]
	global_store_dwordx4 v[76:77], v[62:65], off offset:2048
	global_load_dwordx4 v[62:65], v[10:11], off
	v_mov_b32_e32 v88, v93
	v_mov_b32_e32 v89, v69
	v_mov_b32_e32 v86, v92
	v_mov_b32_e32 v87, v68
	v_pk_mul_f32 v[88:89], v[88:89], v[88:89]
	s_nop 0
	v_pk_fma_f32 v[72:73], v[86:87], v[86:87], v[88:89]
	v_pk_add_f32 v[86:87], v[128:129], v[114:115]
	v_pk_mul_f32 v[114:115], v[74:75], v[54:55] op_sel_hi:[0,1]
	v_pk_mul_f32 v[54:55], v[74:75], v[56:57] op_sel_hi:[0,1]
	v_pk_add_f32 v[70:71], v[70:71], v[72:73]
	v_pk_add_f32 v[72:73], v[86:87], v[86:87] op_sel:[0,1] op_sel_hi:[1,0]
	v_pk_add_f32 v[70:71], v[70:71], v[70:71] op_sel:[0,1] op_sel_hi:[1,0]
	v_mov_b32_e32 v73, v127
	v_mov_b32_e32 v71, v85
	v_pk_add_f32 v[86:87], v[112:113], v[116:117]
	v_pk_add_f32 v[88:89], v[118:119], v[122:123]
	v_pk_add_f32 v[112:113], v[120:121], v[124:125]
	v_pk_add_f32 v[88:89], v[88:89], v[88:89] op_sel:[0,1] op_sel_hi:[1,0]
	s_waitcnt vmcnt(0)
	v_pk_mul_f32 v[54:55], v[54:55], v[62:63]
	v_pk_mul_f32 v[56:57], v[114:115], v[64:65]
	global_store_dwordx4 v[76:77], v[54:57], off offset:3072
	global_load_dwordx4 v[62:65], v[2:3], off
	v_mov_b32_e32 v89, v133
	v_pk_add_f32 v[54:55], v[70:71], v[72:73]
	v_cvt_f32_f16_e32 v72, v46
	v_pk_add_f32 v[54:55], v[54:55], v[86:87]
	v_cvt_f32_f16_sdwa v73, v46 dst_sel:DWORD dst_unused:UNUSED_PAD src0_sel:WORD_1
	v_pk_add_f32 v[54:55], v[54:55], v[54:55] op_sel:[0,1] op_sel_hi:[1,0]
	v_cvt_f32_f16_e32 v76, v44
	v_mov_b32_e32 v55, v132
	v_pk_add_f32 v[54:55], v[54:55], v[88:89]
	v_cvt_f32_f16_sdwa v77, v44 dst_sel:DWORD dst_unused:UNUSED_PAD src0_sel:WORD_1
	v_pk_add_f32 v[54:55], v[54:55], v[112:113]
	v_cvt_f32_f16_e32 v86, v45
	v_add_f32_e32 v54, v54, v55
	v_cvt_f32_f16_sdwa v87, v45 dst_sel:DWORD dst_unused:UNUSED_PAD src0_sel:WORD_1
	v_cvt_f32_f16_e32 v88, v42
	v_cvt_f32_f16_sdwa v89, v42 dst_sel:DWORD dst_unused:UNUSED_PAD src0_sel:WORD_1
	s_waitcnt lgkmcnt(0)
	s_nop 1
	v_add_f32_dpp v54, v54, v54 quad_perm:[1,0,3,2] row_mask:0xf bank_mask:0xf
	v_mul_f32_e32 v74, v89, v89
	s_waitcnt lgkmcnt(0)
	s_nop 1
	v_add_f32_dpp v54, v54, v54 quad_perm:[2,3,0,1] row_mask:0xf bank_mask:0xf
	s_waitcnt lgkmcnt(0)
	s_nop 1
	v_add_f32_dpp v54, v54, v54 row_half_mirror row_mask:0xf bank_mask:0xf
	s_waitcnt lgkmcnt(0)
	s_nop 1
	v_add_f32_dpp v54, v54, v54 row_mirror row_mask:0xf bank_mask:0xf
	s_waitcnt lgkmcnt(0)
	v_mov_b32_e32 v55, v54
	s_nop 1
	v_permlane16_swap_b32_e32 v54, v55
	s_nop 0
	v_add_f32_e32 v54, v54, v55
	s_waitcnt lgkmcnt(0)
	v_mov_b32_e32 v55, v54
	s_nop 1
	v_permlane32_swap_b32_e32 v54, v55
	s_nop 0
	v_add_f32_e32 v54, v54, v55
	v_fmamk_f32 v54, v54, 0x3a000000, v84
	v_rsq_f32_e32 v54, v54
	s_nop 0
	v_pk_mul_f32 v[56:57], v[54:55], v[92:93] op_sel_hi:[0,1]
	v_pk_mul_f32 v[70:71], v[54:55], v[94:95] op_sel_hi:[0,1]
	v_pk_mul_f32 v[66:67], v[54:55], v[66:67] op_sel_hi:[0,1]
	v_pk_mul_f32 v[44:45], v[54:55], v[58:59] op_sel_hi:[0,1]
	v_cvt_f32_f16_sdwa v93, v36 dst_sel:DWORD dst_unused:UNUSED_PAD src0_sel:WORD_1
	v_cvt_f32_f16_sdwa v95, v37 dst_sel:DWORD dst_unused:UNUSED_PAD src0_sel:WORD_1
	v_cvt_f32_f16_e32 v92, v36
	v_cvt_f32_f16_e32 v94, v37
	v_cvt_f32_f16_e32 v58, v43
	v_cvt_f32_f16_sdwa v59, v43 dst_sel:DWORD dst_unused:UNUSED_PAD src0_sel:WORD_1
	v_cvt_f32_f16_sdwa v37, v35 dst_sel:DWORD dst_unused:UNUSED_PAD src0_sel:WORD_1
	v_cvt_f32_f16_e32 v36, v35
	v_cvt_f32_f16_sdwa v35, v34 dst_sel:DWORD dst_unused:UNUSED_PAD src0_sel:WORD_1
	v_cvt_f32_f16_e32 v34, v34
	v_mul_f32_e32 v121, v37, v37
	v_mul_f32_e32 v120, v36, v36
	v_mul_f32_e32 v119, v35, v35
	v_mul_f32_e32 v118, v34, v34
	s_waitcnt vmcnt(0)
	v_pk_mul_f32 v[62:63], v[62:63], v[70:71]
	v_pk_mul_f32 v[64:65], v[64:65], v[56:57]
	global_store_dwordx4 v[90:91], v[62:65], off
	global_load_dwordx4 v[62:65], v[2:3], off offset:1024
	v_pk_mul_f32 v[56:57], v[54:55], v[68:69] op_sel_hi:[0,1]
	v_pk_mul_f32 v[68:69], v[54:55], v[96:97] op_sel_hi:[0,1]
	v_cvt_f32_f16_e32 v70, v48
	v_cvt_f32_f16_sdwa v71, v48 dst_sel:DWORD dst_unused:UNUSED_PAD src0_sel:WORD_1
	v_cvt_f32_f16_e32 v48, v47
	v_mov_b32_e32 v43, v48
	s_waitcnt vmcnt(0)
	v_pk_mul_f32 v[62:63], v[62:63], v[68:69]
	v_pk_mul_f32 v[64:65], v[64:65], v[56:57]
	global_store_dwordx4 v[90:91], v[62:65], off offset:1024
	global_load_dwordx4 v[62:65], v[2:3], off offset:2048
	v_pk_mul_f32 v[56:57], v[54:55], v[98:99] op_sel_hi:[0,1]
	v_pk_mul_f32 v[68:69], v[54:55], v[106:107] op_sel_hi:[0,1]
	v_pk_mul_f32 v[98:99], v[86:87], v[86:87]
	s_waitcnt vmcnt(0)
	v_pk_mul_f32 v[62:63], v[62:63], v[66:67]
	v_pk_mul_f32 v[64:65], v[64:65], v[56:57]
	global_store_dwordx4 v[90:91], v[62:65], off offset:2048
	global_load_dwordx4 v[62:65], v[2:3], off offset:3072
	v_pk_mul_f32 v[56:57], v[54:55], v[102:103] op_sel_hi:[0,1]
	v_pk_mul_f32 v[66:67], v[54:55], v[100:101] op_sel_hi:[0,1]
	v_pk_mul_f32 v[100:101], v[76:77], v[76:77]
	v_mul_f32_e32 v102, v59, v59
	v_pk_mov_b32 v[112:113], v[100:101], v[98:99] op_sel:[1,0]
	v_mov_b32_e32 v101, v99
	v_pk_add_f32 v[100:101], v[112:113], v[100:101]
	v_pk_fma_f32 v[98:99], v[88:89], v[88:89], v[74:75] op_sel_hi:[1,1,0]
	v_pk_fma_f32 v[102:103], v[58:59], v[58:59], v[102:103] op_sel_hi:[1,1,0]
	s_waitcnt vmcnt(0)
	v_pk_mul_f32 v[62:63], v[62:63], v[66:67]
	v_pk_mul_f32 v[64:65], v[64:65], v[56:57]
	global_store_dwordx4 v[90:91], v[62:65], off offset:3072
	global_load_dwordx4 v[62:65], v[4:5], off
	v_add_co_u32_e32 v56, vcc, s1, v90
	v_pk_mul_f32 v[66:67], v[54:55], v[104:105] op_sel_hi:[0,1]
	s_nop 0
	v_addc_co_u32_e32 v57, vcc, 0, v91, vcc
	v_cvt_f32_f16_e32 v90, v39
	v_cvt_f32_f16_sdwa v91, v39 dst_sel:DWORD dst_unused:UNUSED_PAD src0_sel:WORD_1
	v_mov_b32_e32 v39, v72
	v_pk_mul_f32 v[104:105], v[90:91], v[90:91]
	s_waitcnt vmcnt(0)
	v_pk_mul_f32 v[62:63], v[68:69], v[62:63]
	v_pk_mul_f32 v[64:65], v[66:67], v[64:65]
	global_store_dwordx4 v[56:57], v[62:65], off
	global_load_dwordx4 v[62:65], v[6:7], off
	v_pk_mul_f32 v[66:67], v[54:55], v[110:111] op_sel_hi:[0,1]
	v_pk_mul_f32 v[68:69], v[54:55], v[108:109] op_sel_hi:[0,1]
	v_mul_f32_e32 v108, v93, v93
	v_mul_f32_e32 v110, v95, v95
	s_waitcnt vmcnt(0)
	v_pk_mul_f32 v[62:63], v[68:69], v[62:63]
	v_pk_mul_f32 v[64:65], v[66:67], v[64:65]
	global_store_dwordx4 v[56:57], v[62:65], off offset:1024
	global_load_dwordx4 v[62:65], v[8:9], off
	v_cvt_f32_f16_e32 v68, v49
	v_cvt_f32_f16_sdwa v69, v49 dst_sel:DWORD dst_unused:UNUSED_PAD src0_sel:WORD_1
	v_cvt_f32_f16_sdwa v49, v47 dst_sel:DWORD dst_unused:UNUSED_PAD src0_sel:WORD_1
	v_pk_mul_f32 v[46:47], v[54:55], v[60:61] op_sel_hi:[0,1]
	v_cvt_f32_f16_sdwa v61, v41 dst_sel:DWORD dst_unused:UNUSED_PAD src0_sel:WORD_1
	v_cvt_f32_f16_e32 v60, v41
	v_mov_b32_e32 v41, v73
	v_mov_b32_e32 v96, v69
	v_mov_b32_e32 v97, v49
	v_mov_b32_e32 v42, v68
	v_pk_mul_f32 v[96:97], v[96:97], v[96:97]
	v_mul_f32_e32 v116, v60, v60
	v_pk_fma_f32 v[96:97], v[42:43], v[42:43], v[96:97]
	v_mul_f32_e32 v117, v61, v61
	v_mov_b32_e32 v99, v116
	v_mov_b32_e32 v103, v117
	v_lshl_add_u64 v[66:67], v[16:17], 0, s[20:21]
	s_waitcnt vmcnt(0)
	v_pk_mul_f32 v[44:45], v[44:45], v[62:63]
	v_pk_mul_f32 v[46:47], v[46:47], v[64:65]
	global_store_dwordx4 v[56:57], v[44:47], off offset:2048
	global_load_dwordx4 v[44:47], v[10:11], off
	v_cvt_f32_f16_e32 v62, v40
	v_cvt_f32_f16_e32 v64, v38
	v_cvt_f32_f16_sdwa v65, v38 dst_sel:DWORD dst_unused:UNUSED_PAD src0_sel:WORD_1
	v_cvt_f32_f16_sdwa v63, v40 dst_sel:DWORD dst_unused:UNUSED_PAD src0_sel:WORD_1
	v_mov_b32_e32 v40, v71
	v_mov_b32_e32 v38, v70
	v_mul_f32_e32 v55, v62, v62
	v_pk_mul_f32 v[106:107], v[64:65], v[64:65]
	v_pk_mul_f32 v[40:41], v[40:41], v[40:41]
	v_pk_mov_b32 v[114:115], v[106:107], v[104:105] op_sel:[1,0]
	v_mov_b32_e32 v107, v105
	v_pk_fma_f32 v[104:105], v[92:93], v[92:93], v[108:109] op_sel_hi:[1,1,0]
	v_pk_fma_f32 v[108:109], v[94:95], v[94:95], v[110:111] op_sel_hi:[1,1,0]
	v_pk_fma_f32 v[110:111], v[38:39], v[38:39], v[40:41]
	v_pk_mul_f32 v[40:41], v[54:55], v[50:51] op_sel_hi:[0,1]
	v_pk_mul_f32 v[38:39], v[54:55], v[52:53] op_sel_hi:[0,1]
	v_mul_f32_e32 v85, v63, v63
	v_pk_add_f32 v[106:107], v[114:115], v[106:107]
	v_mov_b32_e32 v105, v120
	v_pk_add_f32 v[50:51], v[106:107], v[106:107] op_sel:[0,1] op_sel_hi:[1,0]
	v_mov_b32_e32 v109, v121
	v_mov_b32_e32 v51, v119
	v_pk_add_f32 v[52:53], v[104:105], v[108:109]
	v_cvt_f32_f16_e32 v54, v26
	s_waitcnt vmcnt(0)
	v_pk_mul_f32 v[38:39], v[38:39], v[44:45]
	v_pk_mul_f32 v[40:41], v[40:41], v[46:47]
	global_store_dwordx4 v[56:57], v[38:41], off offset:3072
	global_load_dwordx4 v[40:43], v[2:3], off
	v_pk_add_f32 v[44:45], v[100:101], v[100:101] op_sel:[0,1] op_sel_hi:[1,0]
	v_pk_add_f32 v[38:39], v[110:111], v[96:97]
	v_mov_b32_e32 v45, v85
	v_pk_add_f32 v[38:39], v[38:39], v[38:39] op_sel:[0,1] op_sel_hi:[1,0]
	v_pk_add_f32 v[46:47], v[98:99], v[102:103]
	v_mov_b32_e32 v39, v55
	v_pk_add_f32 v[38:39], v[38:39], v[44:45]
	v_cvt_f32_f16_sdwa v57, v25 dst_sel:DWORD dst_unused:UNUSED_PAD src0_sel:WORD_1
	v_pk_add_f32 v[38:39], v[38:39], v[46:47]
	v_cvt_f32_f16_e32 v56, v25
	v_pk_add_f32 v[38:39], v[38:39], v[38:39] op_sel:[0,1] op_sel_hi:[1,0]
	v_cvt_f32_f16_sdwa v25, v24 dst_sel:DWORD dst_unused:UNUSED_PAD src0_sel:WORD_1
	v_mov_b32_e32 v39, v118
	v_pk_add_f32 v[38:39], v[38:39], v[50:51]
	v_cvt_f32_f16_sdwa v51, v32 dst_sel:DWORD dst_unused:UNUSED_PAD src0_sel:WORD_1
	v_pk_add_f32 v[38:39], v[38:39], v[52:53]
	v_cvt_f32_f16_sdwa v53, v30 dst_sel:DWORD dst_unused:UNUSED_PAD src0_sel:WORD_1
	v_add_f32_e32 v38, v38, v39
	v_cvt_f32_f16_e32 v50, v32
	v_cvt_f32_f16_e32 v32, v31
	v_cvt_f32_f16_e32 v52, v30
	v_cvt_f32_f16_e32 v30, v28
	s_waitcnt lgkmcnt(0)
	s_nop 1
	v_add_f32_dpp v38, v38, v38 quad_perm:[1,0,3,2] row_mask:0xf bank_mask:0xf
	v_cvt_f32_f16_sdwa v55, v26 dst_sel:DWORD dst_unused:UNUSED_PAD src0_sel:WORD_1
	v_cvt_f32_f16_e32 v26, v27
	v_cvt_f32_f16_sdwa v27, v27 dst_sel:DWORD dst_unused:UNUSED_PAD src0_sel:WORD_1
	v_cvt_f32_f16_e32 v24, v24
	s_waitcnt lgkmcnt(0)
	s_nop 1
	v_add_f32_dpp v38, v38, v38 quad_perm:[2,3,0,1] row_mask:0xf bank_mask:0xf
	v_mul_f32_e32 v74, v55, v55
	v_mul_f32_e32 v85, v24, v24
	v_mul_f32_e32 v104, v57, v57
	s_waitcnt lgkmcnt(0)
	s_nop 1
	v_add_f32_dpp v38, v38, v38 row_half_mirror row_mask:0xf bank_mask:0xf
	s_waitcnt lgkmcnt(0)
	s_nop 1
	v_add_f32_dpp v38, v38, v38 row_mirror row_mask:0xf bank_mask:0xf
	s_waitcnt lgkmcnt(0)
	v_mov_b32_e32 v39, v38
	s_nop 1
	v_permlane16_swap_b32_e32 v38, v39
	s_nop 0
	v_add_f32_e32 v38, v38, v39
	s_waitcnt lgkmcnt(0)
	v_mov_b32_e32 v39, v38
	s_nop 1
	v_permlane32_swap_b32_e32 v38, v39
	s_nop 0
	v_add_f32_e32 v38, v38, v39
	v_fmamk_f32 v38, v38, 0x3a000000, v84
	v_rsq_f32_e32 v38, v38
	s_nop 0
	v_pk_mul_f32 v[44:45], v[38:39], v[68:69] op_sel_hi:[0,1]
	v_pk_mul_f32 v[46:47], v[38:39], v[70:71] op_sel_hi:[0,1]
	v_mov_b32_e32 v68, v50
	v_mov_b32_e32 v69, v52
	v_mov_b32_e32 v71, v32
	s_waitcnt vmcnt(0)
	v_pk_mul_f32 v[40:41], v[40:41], v[46:47]
	v_pk_mul_f32 v[42:43], v[42:43], v[44:45]
	global_store_dwordx4 v[66:67], v[40:43], off
	global_load_dwordx4 v[40:43], v[2:3], off offset:1024
	v_pk_mul_f32 v[44:45], v[38:39], v[48:49] op_sel_hi:[0,1]
	v_pk_mul_f32 v[46:47], v[38:39], v[72:73] op_sel_hi:[0,1]
	v_pk_mul_f32 v[48:49], v[38:39], v[62:63] op_sel_hi:[0,1]
	v_cvt_f32_f16_e32 v62, v21
	v_cvt_f32_f16_sdwa v63, v21 dst_sel:DWORD dst_unused:UNUSED_PAD src0_sel:WORD_1
	s_waitcnt vmcnt(0)
	v_pk_mul_f32 v[40:41], v[40:41], v[46:47]
	v_pk_mul_f32 v[42:43], v[42:43], v[44:45]
	global_store_dwordx4 v[66:67], v[40:43], off offset:1024
	global_load_dwordx4 v[40:43], v[2:3], off offset:2048
	v_pk_mul_f32 v[44:45], v[38:39], v[86:87] op_sel_hi:[0,1]
	v_pk_mul_f32 v[46:47], v[38:39], v[76:77] op_sel_hi:[0,1]
	v_mul_f32_e32 v86, v27, v27
	v_pk_fma_f32 v[86:87], v[26:27], v[26:27], v[86:87] op_sel_hi:[1,1,0]
	s_waitcnt vmcnt(0)
	v_pk_mul_f32 v[40:41], v[40:41], v[46:47]
	v_pk_mul_f32 v[42:43], v[42:43], v[44:45]
	global_store_dwordx4 v[66:67], v[40:43], off offset:2048
	global_load_dwordx4 v[40:43], v[2:3], off offset:3072
	v_pk_mul_f32 v[44:45], v[38:39], v[58:59] op_sel_hi:[0,1]
	v_pk_mul_f32 v[46:47], v[38:39], v[88:89] op_sel_hi:[0,1]
	v_cvt_f32_f16_e32 v58, v22
	v_cvt_f32_f16_sdwa v59, v22 dst_sel:DWORD dst_unused:UNUSED_PAD src0_sel:WORD_1
	v_cvt_f32_f16_e32 v22, v23
	v_cvt_f32_f16_sdwa v23, v23 dst_sel:DWORD dst_unused:UNUSED_PAD src0_sel:WORD_1
	v_mov_b32_e32 v87, v104
	v_pk_mul_f32 v[88:89], v[22:23], v[22:23]
	s_waitcnt vmcnt(0)
	v_pk_mul_f32 v[40:41], v[40:41], v[46:47]
	v_pk_mul_f32 v[42:43], v[42:43], v[44:45]
	global_store_dwordx4 v[66:67], v[40:43], off offset:3072
	global_load_dwordx4 v[42:45], v[4:5], off
	v_pk_mul_f32 v[46:47], v[38:39], v[60:61] op_sel_hi:[0,1]
	v_add_co_u32_e32 v40, vcc, s1, v66
	v_cvt_f32_f16_e32 v60, v20
	s_nop 0
	v_addc_co_u32_e32 v41, vcc, 0, v67, vcc
	v_cvt_f32_f16_sdwa v61, v20 dst_sel:DWORD dst_unused:UNUSED_PAD src0_sel:WORD_1
	v_cvt_f32_f16_sdwa v67, v18 dst_sel:DWORD dst_unused:UNUSED_PAD src0_sel:WORD_1
	v_cvt_f32_f16_e32 v66, v18
	v_mov_b32_e32 v18, v51
	v_mul_f32_e32 v106, v67, v67
	v_mul_f32_e32 v105, v66, v66
	s_waitcnt vmcnt(0)
	v_pk_mul_f32 v[42:43], v[48:49], v[42:43]
	v_pk_mul_f32 v[44:45], v[46:47], v[44:45]
	global_store_dwordx4 v[40:41], v[42:45], off
	global_load_dwordx4 v[42:45], v[6:7], off
	v_pk_mul_f32 v[46:47], v[38:39], v[90:91] op_sel_hi:[0,1]
	v_pk_mul_f32 v[48:49], v[38:39], v[64:65] op_sel_hi:[0,1]
	v_cvt_f32_f16_sdwa v65, v19 dst_sel:DWORD dst_unused:UNUSED_PAD src0_sel:WORD_1
	v_cvt_f32_f16_e32 v64, v19
	v_mov_b32_e32 v19, v53
	v_pk_mul_f32 v[96:97], v[18:19], v[18:19]
	v_pk_mul_f32 v[18:19], v[38:39], v[34:35] op_sel_hi:[0,1]
	v_mul_f32_e32 v107, v64, v64
	v_mul_f32_e32 v108, v65, v65
	v_pk_mul_f32 v[90:91], v[58:59], v[58:59]
	s_waitcnt vmcnt(0)
	v_pk_mul_f32 v[42:43], v[48:49], v[42:43]
	v_pk_mul_f32 v[44:45], v[46:47], v[44:45]
	global_store_dwordx4 v[40:41], v[42:45], off offset:1024
	global_load_dwordx4 v[42:45], v[8:9], off
	v_pk_mul_f32 v[46:47], v[38:39], v[94:95] op_sel_hi:[0,1]
	v_pk_mul_f32 v[48:49], v[38:39], v[92:93] op_sel_hi:[0,1]
	v_mul_f32_e32 v93, v25, v25
	v_mul_f32_e32 v95, v56, v56
	v_mul_f32_e32 v92, v61, v61
	v_mul_f32_e32 v94, v63, v63
	v_pk_fma_f32 v[34:35], v[60:61], v[60:61], v[92:93] op_sel_hi:[1,1,0]
	v_pk_mov_b32 v[102:103], v[90:91], v[88:89] op_sel:[1,0]
	v_mov_b32_e32 v35, v107
	v_mov_b32_e32 v91, v89
	s_waitcnt vmcnt(0)
	v_pk_mul_f32 v[42:43], v[48:49], v[42:43]
	v_pk_mul_f32 v[44:45], v[46:47], v[44:45]
	global_store_dwordx4 v[40:41], v[42:45], off offset:2048
	global_load_dwordx4 v[42:45], v[10:11], off
	v_cvt_f32_f16_e32 v48, v33
	v_cvt_f32_f16_sdwa v49, v33 dst_sel:DWORD dst_unused:UNUSED_PAD src0_sel:WORD_1
	v_cvt_f32_f16_sdwa v33, v31 dst_sel:DWORD dst_unused:UNUSED_PAD src0_sel:WORD_1
	v_cvt_f32_f16_sdwa v31, v28 dst_sel:DWORD dst_unused:UNUSED_PAD src0_sel:WORD_1
	v_cvt_f32_f16_e32 v28, v29
	v_mov_b32_e32 v20, v49
	v_mov_b32_e32 v21, v33
	v_pk_mul_f32 v[98:99], v[20:21], v[20:21]
	v_pk_mul_f32 v[20:21], v[38:39], v[36:37] op_sel_hi:[0,1]
	v_cvt_f32_f16_sdwa v29, v29 dst_sel:DWORD dst_unused:UNUSED_PAD src0_sel:WORD_1
	v_mov_b32_e32 v70, v48
	v_pk_mul_f32 v[76:77], v[30:31], v[30:31]
	v_pk_fma_f32 v[36:37], v[62:63], v[62:63], v[94:95] op_sel_hi:[1,1,0]
	v_pk_mul_f32 v[72:73], v[28:29], v[28:29]
	v_pk_fma_f32 v[38:39], v[68:69], v[68:69], v[96:97]
	v_pk_mov_b32 v[100:101], v[76:77], v[72:73] op_sel:[1,0]
	v_mov_b32_e32 v77, v73
	v_mov_b32_e32 v37, v108
	v_pk_fma_f32 v[72:73], v[54:55], v[54:55], v[74:75] op_sel_hi:[1,1,0]
	v_pk_add_f32 v[34:35], v[34:35], v[36:37]
	v_mov_b32_e32 v73, v95
	v_lshl_add_u64 v[46:47], v[16:17], 0, s[18:19]
	s_cselect_b64 s[18:19], -1, 0
	s_add_u32 s6, s6, s8
	s_addc_u32 s7, s7, s9
	s_add_u32 s10, s10, s12
	s_addc_u32 s11, s11, s13
	s_add_u32 s14, s14, s8
	s_addc_u32 s15, s15, s9
	s_add_u32 s16, s16, s12
	s_addc_u32 s17, s17, s13
	s_waitcnt vmcnt(0)
	v_pk_mul_f32 v[18:19], v[18:19], v[42:43]
	v_pk_mul_f32 v[20:21], v[20:21], v[44:45]
	global_store_dwordx4 v[40:41], v[18:21], off offset:3072
	global_load_dwordx4 v[18:21], v[2:3], off
	v_pk_fma_f32 v[40:41], v[70:71], v[70:71], v[98:99]
	v_pk_add_f32 v[42:43], v[100:101], v[76:77]
	v_pk_add_f32 v[38:39], v[38:39], v[40:41]
	v_pk_add_f32 v[40:41], v[42:43], v[42:43] op_sel:[0,1] op_sel_hi:[1,0]
	v_pk_add_f32 v[36:37], v[38:39], v[38:39] op_sel:[0,1] op_sel_hi:[1,0]
	v_mov_b32_e32 v41, v93
	v_mov_b32_e32 v37, v85
	v_pk_add_f32 v[42:43], v[72:73], v[86:87]
	v_pk_add_f32 v[36:37], v[36:37], v[40:41]
	v_pk_add_f32 v[44:45], v[102:103], v[90:91]
	v_pk_add_f32 v[36:37], v[36:37], v[42:43]
	v_pk_add_f32 v[44:45], v[44:45], v[44:45] op_sel:[0,1] op_sel_hi:[1,0]
	v_pk_add_f32 v[36:37], v[36:37], v[36:37] op_sel:[0,1] op_sel_hi:[1,0]
	v_mov_b32_e32 v45, v106
	v_mov_b32_e32 v37, v105
	v_pk_add_f32 v[36:37], v[36:37], v[44:45]
	s_nop 0
	v_pk_add_f32 v[34:35], v[36:37], v[34:35]
	s_nop 0
	v_add_f32_e32 v34, v34, v35
	s_waitcnt lgkmcnt(0)
	s_nop 1
	v_add_f32_dpp v34, v34, v34 quad_perm:[1,0,3,2] row_mask:0xf bank_mask:0xf
	s_waitcnt lgkmcnt(0)
	s_nop 1
	v_add_f32_dpp v34, v34, v34 quad_perm:[2,3,0,1] row_mask:0xf bank_mask:0xf
	s_waitcnt lgkmcnt(0)
	s_nop 1
	v_add_f32_dpp v34, v34, v34 row_half_mirror row_mask:0xf bank_mask:0xf
	s_waitcnt lgkmcnt(0)
	s_nop 1
	v_add_f32_dpp v34, v34, v34 row_mirror row_mask:0xf bank_mask:0xf
	s_waitcnt lgkmcnt(0)
	v_mov_b32_e32 v35, v34
	s_nop 1
	v_permlane16_swap_b32_e32 v34, v35
	s_nop 0
	v_add_f32_e32 v34, v34, v35
	s_waitcnt lgkmcnt(0)
	v_mov_b32_e32 v35, v34
	s_nop 1
	v_permlane32_swap_b32_e32 v34, v35
	s_nop 0
	v_add_f32_e32 v34, v34, v35
	v_fmamk_f32 v34, v34, 0x3a000000, v84
	v_rsq_f32_e32 v34, v34
	s_nop 0
	v_pk_mul_f32 v[36:37], v[34:35], v[48:49] op_sel_hi:[0,1]
	v_pk_mul_f32 v[38:39], v[34:35], v[50:51] op_sel_hi:[0,1]
	v_pk_mul_f32 v[32:33], v[34:35], v[32:33] op_sel_hi:[0,1]
	v_pk_mul_f32 v[28:29], v[34:35], v[28:29] op_sel_hi:[0,1]
	v_pk_mul_f32 v[30:31], v[34:35], v[30:31] op_sel_hi:[0,1]
	v_pk_mul_f32 v[26:27], v[34:35], v[26:27] op_sel_hi:[0,1]
	v_pk_mul_f32 v[24:25], v[34:35], v[24:25] op_sel_hi:[0,1]
	v_pk_mul_f32 v[22:23], v[34:35], v[22:23] op_sel_hi:[0,1]
	s_waitcnt vmcnt(0)
	v_pk_mul_f32 v[18:19], v[18:19], v[38:39]
	v_pk_mul_f32 v[20:21], v[20:21], v[36:37]
	global_store_dwordx4 v[46:47], v[18:21], off
	global_load_dwordx4 v[18:21], v[2:3], off offset:1024
	v_pk_mul_f32 v[36:37], v[34:35], v[52:53] op_sel_hi:[0,1]
	s_waitcnt vmcnt(0)
	v_pk_mul_f32 v[18:19], v[18:19], v[36:37]
	v_pk_mul_f32 v[20:21], v[20:21], v[32:33]
	global_store_dwordx4 v[46:47], v[18:21], off offset:1024
	global_load_dwordx4 v[18:21], v[2:3], off offset:2048
	s_waitcnt vmcnt(0)
	v_pk_mul_f32 v[18:19], v[18:19], v[30:31]
	v_pk_mul_f32 v[20:21], v[20:21], v[28:29]
	global_store_dwordx4 v[46:47], v[18:21], off offset:2048
	global_load_dwordx4 v[18:21], v[2:3], off offset:3072
	v_pk_mul_f32 v[28:29], v[34:35], v[54:55] op_sel_hi:[0,1]
	s_waitcnt vmcnt(0)
	v_pk_mul_f32 v[18:19], v[18:19], v[28:29]
	v_pk_mul_f32 v[20:21], v[20:21], v[26:27]
	global_store_dwordx4 v[46:47], v[18:21], off offset:3072
	global_load_dwordx4 v[18:21], v[4:5], off
	v_add_co_u32_e32 v26, vcc, s1, v46
	v_pk_mul_f32 v[28:29], v[34:35], v[56:57] op_sel_hi:[0,1]
	s_nop 0
	v_addc_co_u32_e32 v27, vcc, 0, v47, vcc
	v_subrev_co_u32_e32 v83, vcc, 1, v83
	s_waitcnt vmcnt(0)
	v_pk_mul_f32 v[18:19], v[24:25], v[18:19]
	v_pk_mul_f32 v[20:21], v[28:29], v[20:21]
	global_store_dwordx4 v[26:27], v[18:21], off
	global_load_dwordx4 v[18:21], v[6:7], off
	v_pk_mul_f32 v[24:25], v[34:35], v[58:59] op_sel_hi:[0,1]
	s_waitcnt vmcnt(0)
	v_pk_mul_f32 v[18:19], v[24:25], v[18:19]
	v_pk_mul_f32 v[20:21], v[22:23], v[20:21]
	global_store_dwordx4 v[26:27], v[18:21], off offset:1024
	global_load_dwordx4 v[18:21], v[8:9], off
	v_pk_mul_f32 v[22:23], v[34:35], v[62:63] op_sel_hi:[0,1]
	v_pk_mul_f32 v[24:25], v[34:35], v[60:61] op_sel_hi:[0,1]
	s_waitcnt vmcnt(0)
	v_pk_mul_f32 v[18:19], v[24:25], v[18:19]
	v_pk_mul_f32 v[20:21], v[22:23], v[20:21]
	global_store_dwordx4 v[26:27], v[18:21], off offset:2048
	global_load_dwordx4 v[18:21], v[10:11], off
	v_cndmask_b32_e64 v22, 0, 1, vcc
	v_cndmask_b32_e64 v23, 0, 1, s[18:19]
	v_cndmask_b32_e64 v22, v23, v22, s[2:3]
	v_and_b32_e32 v22, 1, v22
	v_cmp_eq_u32_e32 vcc, 1, v22
	v_pk_mul_f32 v[22:23], v[34:35], v[64:65] op_sel_hi:[0,1]
	v_pk_mul_f32 v[24:25], v[34:35], v[66:67] op_sel_hi:[0,1]
	s_and_b64 vcc, exec, vcc
	s_waitcnt vmcnt(0)
	v_pk_mul_f32 v[18:19], v[24:25], v[18:19]
	v_pk_mul_f32 v[20:21], v[22:23], v[20:21]
	global_store_dwordx4 v[26:27], v[18:21], off offset:3072
	s_cbranch_vccnz .LBB0_2205
